# also dropped the redundant lgkmcnt(0) between mainloop barrier and first MFMA
# baseline (speedup 1.0000x reference)
; #define PG8_STAGE(bufoff, gbase, voff) do { _Pragma("unroll") for (int _i = 0; _i < 2; ++_i) \
;         __builtin_amdgcn_global_load_lds((const unsigned*)((const char*)(gbase) + (voff)[_i]), (LAS unsigned*)(lds + (bufoff) + ldsw + _i * 8192), 16, 0, 0); } while (0)
; #define PG8_LDA(dst, b, h) do { _Pragma("unroll") for (int m = 0; m < 4; ++m) _Pragma("unroll") for (int k = 0; k < 2; ++k) dst[m][k] = *(const LAS bf16x8*)(lds + PG8_SA(b, h) + aoff + m * 2048 + k * 1024); } while (0)
; #define PG8_LDB(dst, b, h) do { _Pragma("unroll") for (int n = 0; n < 2; ++n) _Pragma("unroll") for (int k = 0; k < 2; ++k) dst[n][k] = *(const LAS bf16x8*)(lds + PG8_SB(b, h) + boff + n * 2048 + k * 1024); } while (0)
; #define PG8_MMA(ai, bj, At, Bt) do { __builtin_amdgcn_s_setprio(1); _Pragma("unroll") for (int m = 0; m < 4; ++m) _Pragma("unroll") for (int n = 0; n < 2; ++n) _Pragma("unroll") for (int k = 0; k < 2; ++k) \
;         acc[ai][bj][m][n] = __builtin_amdgcn_mfma_f32_16x16x32_bf16(Bt[n][k], At[m][k], acc[ai][bj][m][n], 0, 0, 0); __builtin_amdgcn_s_setprio(0); } while (0)
; #define PG8_WAIT_V(n) asm volatile("s_waitcnt vmcnt(" #n ")" ::: "memory")
; #define PG8_WAIT_L(n) asm volatile("s_waitcnt lgkmcnt(" #n ")" ::: "memory")
; #define PG8_BAR __builtin_amdgcn_s_barrier()
; #define PG8_SCHED __builtin_amdgcn_sched_barrier(0)
; template <class Epi, bool ALIGN_EPI, bool SP2 = PG8_SP2_DEFAULT>
; __device__ __forceinline__ void gemm_phase(LAS unsigned char* lds, const Gemm g, const StaticOrder& S, const Epi& E) {
;     ...
;             PG8_LDB(B0, 0, 0); PG8_LDB(B1, 0, 1); PG8_SCHED; PG8_LDA(At, 0, 0); PG8_STAGE(PG8_SA(1, 1), a1 + hstepA, voffA);
;             PG8_WAIT_V(8); PG8_WAIT_L(0); PG8_BAR; PG8_MMA(0, 0, At, B0); PG8_MMA(0, 1, At, B1); PG8_BAR; PG8_SCHED;
;             PG8_LDA(At, 0, 1); PG8_STAGE(PG8_SB(0, 0), b2, voffB); PG8_STAGE(PG8_SB(0, 1), b2 + hstepB, voffB); PG8_STAGE(PG8_SA(0, 0), a2, voffA);
.LBB0_250:
	ds_read_b128 v[150:153], v147
	ds_read_b128 v[154:157], v147 offset:1024
	ds_read_b128 v[158:161], v147 offset:2048
	ds_read_b128 v[162:165], v147 offset:3072
	ds_read_b128 v[166:169], v148
	ds_read_b128 v[170:173], v148 offset:1024
	ds_read_b128 v[174:177], v148 offset:2048
	ds_read_b128 v[178:181], v148 offset:3072
	s_add_u32 s20, s18, 0xfff00080
	s_addc_u32 s21, s19, -1
	s_cmp_eq_u32 s44, 60
	s_cselect_b32 s23, s13, s21
	s_cselect_b32 s22, s40, s20
	s_cselect_b32 s21, s11, s43
	s_cselect_b32 s20, s41, s42
	v_lshl_add_u64 v[206:207], s[18:19], 0, v[136:137]
	s_add_i32 m0, s9, 0xc000
	ds_read_b128 v[182:185], v149
	ds_read_b128 v[186:189], v149 offset:1024
	ds_read_b128 v[190:193], v149 offset:2048
	ds_read_b128 v[198:201], v149 offset:3072
	ds_read_b128 v[202:205], v149 offset:4096
	ds_read_b128 v[216:219], v149 offset:5120
	ds_read_b128 v[220:223], v149 offset:6144
	ds_read_b128 v[224:227], v149 offset:7168
	global_load_lds_dwordx4 v[206:207], off
	v_lshl_add_u64 v[206:207], s[18:19], 0, v[138:139]
	s_add_i32 m0, s9, 0xe000
	s_nop 0
	global_load_lds_dwordx4 v[206:207], off
	s_waitcnt vmcnt(8)
	s_waitcnt lgkmcnt(0)
	s_barrier
	v_mfma_f32_16x16x32_bf16 v[124:127], v[150:153], v[182:185], v[124:127]
	v_mfma_f32_16x16x32_bf16 v[120:123], v[158:161], v[182:185], v[120:123]
	v_mfma_f32_16x16x32_bf16 v[116:119], v[150:153], v[190:193], v[116:119]
	v_mfma_f32_16x16x32_bf16 v[112:115], v[158:161], v[190:193], v[112:115]
	v_mfma_f32_16x16x32_bf16 v[100:103], v[150:153], v[202:205], v[100:103]
	v_mfma_f32_16x16x32_bf16 v[96:99], v[158:161], v[202:205], v[96:99]
	v_mfma_f32_16x16x32_bf16 v[84:87], v[150:153], v[220:223], v[84:87]
	v_mfma_f32_16x16x32_bf16 v[80:83], v[158:161], v[220:223], v[80:83]
	v_mfma_f32_16x16x32_bf16 v[124:127], v[154:157], v[186:189], v[124:127]
	v_mfma_f32_16x16x32_bf16 v[120:123], v[162:165], v[186:189], v[120:123]
	v_mfma_f32_16x16x32_bf16 v[116:119], v[154:157], v[198:201], v[116:119]
	v_mfma_f32_16x16x32_bf16 v[112:115], v[162:165], v[198:201], v[112:115]
	v_mfma_f32_16x16x32_bf16 v[100:103], v[154:157], v[216:219], v[100:103]
	v_mfma_f32_16x16x32_bf16 v[96:99], v[162:165], v[216:219], v[96:99]
	v_mfma_f32_16x16x32_bf16 v[84:87], v[154:157], v[224:227], v[84:87]
	v_mfma_f32_16x16x32_bf16 v[80:83], v[162:165], v[224:227], v[80:83]
	v_mfma_f32_16x16x32_bf16 v[108:111], v[166:169], v[182:185], v[108:111]
	v_mfma_f32_16x16x32_bf16 v[104:107], v[174:177], v[182:185], v[104:107]
	v_mfma_f32_16x16x32_bf16 v[92:95], v[166:169], v[190:193], v[92:95]
	v_mfma_f32_16x16x32_bf16 v[88:91], v[174:177], v[190:193], v[88:91]
	v_mfma_f32_16x16x32_bf16 v[76:79], v[166:169], v[202:205], v[76:79]
	v_mfma_f32_16x16x32_bf16 v[72:75], v[174:177], v[202:205], v[72:75]
	v_mfma_f32_16x16x32_bf16 v[68:71], v[166:169], v[220:223], v[68:71]
	v_mfma_f32_16x16x32_bf16 v[64:67], v[174:177], v[220:223], v[64:67]
	v_mfma_f32_16x16x32_bf16 v[108:111], v[170:173], v[186:189], v[108:111]
	v_mfma_f32_16x16x32_bf16 v[104:107], v[178:181], v[186:189], v[104:107]
	v_mfma_f32_16x16x32_bf16 v[92:95], v[170:173], v[198:201], v[92:95]
	v_mfma_f32_16x16x32_bf16 v[88:91], v[178:181], v[198:201], v[88:91]
	v_mfma_f32_16x16x32_bf16 v[76:79], v[170:173], v[216:219], v[76:79]
	v_mfma_f32_16x16x32_bf16 v[72:75], v[178:181], v[216:219], v[72:75]
	v_mfma_f32_16x16x32_bf16 v[68:71], v[170:173], v[224:227], v[68:71]
	v_mfma_f32_16x16x32_bf16 v[64:67], v[178:181], v[224:227], v[64:67]
	s_barrier
	s_add_i32 s45, s36, s24
	v_lshl_add_u64 v[206:207], s[20:21], 0, v[132:133]
	s_mov_b32 m0, s45
	ds_read_b128 v[182:185], v149 offset:16384
	ds_read_b128 v[186:189], v149 offset:17408
	ds_read_b128 v[190:193], v149 offset:18432
	ds_read_b128 v[198:201], v149 offset:19456
	ds_read_b128 v[202:205], v149 offset:20480
	ds_read_b128 v[216:219], v149 offset:21504
	ds_read_b128 v[220:223], v149 offset:22528
	ds_read_b128 v[224:227], v149 offset:23552
	global_load_lds_dwordx4 v[206:207], off
	s_add_i32 m0, s45, 0x2000
	s_add_u32 s46, s20, 0x100000
	v_lshl_add_u64 v[210:211], s[20:21], 0, v[128:129]
	s_addc_u32 s47, s21, 0
	s_add_i32 s45, s37, s24
	global_load_lds_dwordx4 v[210:211], off
	v_lshl_add_u64 v[228:229], s[46:47], 0, v[132:133]
	s_mov_b32 m0, s45
	v_lshl_add_u64 v[230:231], s[22:23], 0, v[130:131]
	global_load_lds_dwordx4 v[228:229], off
	v_lshl_add_u64 v[228:229], s[46:47], 0, v[128:129]
	s_add_i32 m0, s45, 0x2000
	s_nop 0
	global_load_lds_dwordx4 v[228:229], off
	v_lshl_add_u64 v[228:229], s[22:23], 0, v[134:135]
	s_mov_b32 m0, s9
	s_nop 0
	global_load_lds_dwordx4 v[228:229], off
	s_mov_b32 m0, s27
	s_nop 0
	global_load_lds_dwordx4 v[230:231], off
	s_waitcnt vmcnt(8)
	s_waitcnt lgkmcnt(0)
	s_barrier
; #define PG8_STAGE(bufoff, gbase, voff) do { _Pragma("unroll") for (int _i = 0; _i < 2; ++_i) \
;         __builtin_amdgcn_global_load_lds((const unsigned*)((const char*)(gbase) + (voff)[_i]), (LAS unsigned*)(lds + (bufoff) + ldsw + _i * 8192), 16, 0, 0); } while (0)
; #define PG8_LDA(dst, b, h) do { _Pragma("unroll") for (int m = 0; m < 4; ++m) _Pragma("unroll") for (int k = 0; k < 2; ++k) dst[m][k] = *(const LAS bf16x8*)(lds + PG8_SA(b, h) + aoff + m * 2048 + k * 1024); } while (0)
; #define PG8_LDB(dst, b, h) do { _Pragma("unroll") for (int n = 0; n < 2; ++n) _Pragma("unroll") for (int k = 0; k < 2; ++k) dst[n][k] = *(const LAS bf16x8*)(lds + PG8_SB(b, h) + boff + n * 2048 + k * 1024); } while (0)
; #define PG8_MMA(ai, bj, At, Bt) do { __builtin_amdgcn_s_setprio(1); _Pragma("unroll") for (int m = 0; m < 4; ++m) _Pragma("unroll") for (int n = 0; n < 2; ++n) _Pragma("unroll") for (int k = 0; k < 2; ++k) \
;         acc[ai][bj][m][n] = __builtin_amdgcn_mfma_f32_16x16x32_bf16(Bt[n][k], At[m][k], acc[ai][bj][m][n], 0, 0, 0); __builtin_amdgcn_s_setprio(0); } while (0)
; #define PG8_WAIT_V(n) asm volatile("s_waitcnt vmcnt(" #n ")" ::: "memory")
; #define PG8_WAIT_L(n) asm volatile("s_waitcnt lgkmcnt(" #n ")" ::: "memory")
; #define PG8_BAR __builtin_amdgcn_s_barrier()
; #define PG8_SCHED __builtin_amdgcn_sched_barrier(0)
; template <class Epi, bool ALIGN_EPI, bool SP2 = PG8_SP2_DEFAULT>
; __device__ __forceinline__ void gemm_phase(LAS unsigned char* lds, const Gemm g, const StaticOrder& S, const Epi& E) {
;     ...
;             PG8_WAIT_V(8); PG8_WAIT_L(0); PG8_BAR; PG8_MMA(1, 0, At, B0); PG8_MMA(1, 1, At, B1); PG8_BAR; PG8_SCHED;
;             PG8_LDB(B0, 1, 0); PG8_LDB(B1, 1, 1); PG8_SCHED; PG8_LDA(At, 1, 0); PG8_STAGE(PG8_SA(0, 1), a2 + hstepA, voffA);
;             PG8_WAIT_V(8); PG8_WAIT_L(0); PG8_BAR; PG8_MMA(0, 0, At, B0); PG8_MMA(0, 1, At, B1); PG8_BAR; PG8_SCHED;
	v_mfma_f32_16x16x32_bf16 v[60:63], v[150:153], v[182:185], v[60:63]
	v_mfma_f32_16x16x32_bf16 v[56:59], v[158:161], v[182:185], v[56:59]
	v_mfma_f32_16x16x32_bf16 v[52:55], v[150:153], v[190:193], v[52:55]
	v_mfma_f32_16x16x32_bf16 v[48:51], v[158:161], v[190:193], v[48:51]
	v_mfma_f32_16x16x32_bf16 v[36:39], v[150:153], v[202:205], v[36:39]
	v_mfma_f32_16x16x32_bf16 v[32:35], v[158:161], v[202:205], v[32:35]
	v_mfma_f32_16x16x32_bf16 v[20:23], v[150:153], v[220:223], v[20:23]
	v_mfma_f32_16x16x32_bf16 v[16:19], v[158:161], v[220:223], v[16:19]
	v_mfma_f32_16x16x32_bf16 v[60:63], v[154:157], v[186:189], v[60:63]
	v_mfma_f32_16x16x32_bf16 v[56:59], v[162:165], v[186:189], v[56:59]
	v_mfma_f32_16x16x32_bf16 v[52:55], v[154:157], v[198:201], v[52:55]
	v_mfma_f32_16x16x32_bf16 v[48:51], v[162:165], v[198:201], v[48:51]
	v_mfma_f32_16x16x32_bf16 v[36:39], v[154:157], v[216:219], v[36:39]
	v_mfma_f32_16x16x32_bf16 v[32:35], v[162:165], v[216:219], v[32:35]
	v_mfma_f32_16x16x32_bf16 v[20:23], v[154:157], v[224:227], v[20:23]
	v_mfma_f32_16x16x32_bf16 v[16:19], v[162:165], v[224:227], v[16:19]
	v_mfma_f32_16x16x32_bf16 v[44:47], v[166:169], v[182:185], v[44:47]
	v_mfma_f32_16x16x32_bf16 v[40:43], v[174:177], v[182:185], v[40:43]
	v_mfma_f32_16x16x32_bf16 v[28:31], v[166:169], v[190:193], v[28:31]
	v_mfma_f32_16x16x32_bf16 v[24:27], v[174:177], v[190:193], v[24:27]
	v_mfma_f32_16x16x32_bf16 v[12:15], v[166:169], v[202:205], v[12:15]
	v_mfma_f32_16x16x32_bf16 v[8:11], v[174:177], v[202:205], v[8:11]
	v_mfma_f32_16x16x32_bf16 v[4:7], v[166:169], v[220:223], v[4:7]
	v_mfma_f32_16x16x32_bf16 v[0:3], v[174:177], v[220:223], v[0:3]
	v_mfma_f32_16x16x32_bf16 v[44:47], v[170:173], v[186:189], v[44:47]
	v_mfma_f32_16x16x32_bf16 v[40:43], v[178:181], v[186:189], v[40:43]
	v_mfma_f32_16x16x32_bf16 v[28:31], v[170:173], v[198:201], v[28:31]
	v_mfma_f32_16x16x32_bf16 v[24:27], v[178:181], v[198:201], v[24:27]
	v_mfma_f32_16x16x32_bf16 v[12:15], v[170:173], v[216:219], v[12:15]
	v_mfma_f32_16x16x32_bf16 v[8:11], v[178:181], v[216:219], v[8:11]
	v_mfma_f32_16x16x32_bf16 v[4:7], v[170:173], v[224:227], v[4:7]
	v_mfma_f32_16x16x32_bf16 v[0:3], v[178:181], v[224:227], v[0:3]
	s_barrier
	s_add_i32 s45, 0, 0x18000
	s_add_i32 s46, 0, 0x1c000
	v_add_u32_e32 v162, s45, v145
	v_add_u32_e32 v178, s46, v145
	ds_read_b128 v[150:153], v162
	ds_read_b128 v[154:157], v162 offset:1024
	ds_read_b128 v[158:161], v162 offset:2048
	ds_read_b128 v[162:165], v162 offset:3072
	ds_read_b128 v[166:169], v178
	ds_read_b128 v[170:173], v178 offset:1024
	ds_read_b128 v[174:177], v178 offset:2048
	ds_read_b128 v[178:181], v178 offset:3072
	s_add_u32 s22, s22, 0x100000
	s_addc_u32 s23, s23, 0
	s_mov_b32 m0, s28
	v_lshl_add_u64 v[232:233], s[22:23], 0, v[134:135]
	ds_read_b128 v[182:185], v149 offset:32768
	ds_read_b128 v[186:189], v149 offset:33792
	ds_read_b128 v[190:193], v149 offset:34816
	ds_read_b128 v[198:201], v149 offset:35840
	ds_read_b128 v[202:205], v149 offset:36864
	ds_read_b128 v[216:219], v149 offset:37888
	ds_read_b128 v[220:223], v149 offset:38912
	ds_read_b128 v[224:227], v149 offset:39936
	global_load_lds_dwordx4 v[232:233], off
	v_lshl_add_u64 v[232:233], s[22:23], 0, v[130:131]
	s_mov_b32 m0, s29
	s_nop 0
	global_load_lds_dwordx4 v[232:233], off
	s_waitcnt vmcnt(8)
	s_waitcnt lgkmcnt(0)
	s_barrier
	v_mfma_f32_16x16x32_bf16 v[124:127], v[150:153], v[182:185], v[124:127]
	v_mfma_f32_16x16x32_bf16 v[120:123], v[158:161], v[182:185], v[120:123]
	v_mfma_f32_16x16x32_bf16 v[116:119], v[150:153], v[190:193], v[116:119]
	v_mfma_f32_16x16x32_bf16 v[112:115], v[158:161], v[190:193], v[112:115]
	v_mfma_f32_16x16x32_bf16 v[100:103], v[150:153], v[202:205], v[100:103]
	v_mfma_f32_16x16x32_bf16 v[96:99], v[158:161], v[202:205], v[96:99]
	v_mfma_f32_16x16x32_bf16 v[84:87], v[150:153], v[220:223], v[84:87]
	v_mfma_f32_16x16x32_bf16 v[80:83], v[158:161], v[220:223], v[80:83]
	v_mfma_f32_16x16x32_bf16 v[124:127], v[154:157], v[186:189], v[124:127]
	v_mfma_f32_16x16x32_bf16 v[120:123], v[162:165], v[186:189], v[120:123]
	v_mfma_f32_16x16x32_bf16 v[116:119], v[154:157], v[198:201], v[116:119]
	v_mfma_f32_16x16x32_bf16 v[112:115], v[162:165], v[198:201], v[112:115]
	v_mfma_f32_16x16x32_bf16 v[100:103], v[154:157], v[216:219], v[100:103]
	v_mfma_f32_16x16x32_bf16 v[96:99], v[162:165], v[216:219], v[96:99]
	v_mfma_f32_16x16x32_bf16 v[84:87], v[154:157], v[224:227], v[84:87]
	v_mfma_f32_16x16x32_bf16 v[80:83], v[162:165], v[224:227], v[80:83]
	v_mfma_f32_16x16x32_bf16 v[108:111], v[166:169], v[182:185], v[108:111]
	v_mfma_f32_16x16x32_bf16 v[104:107], v[174:177], v[182:185], v[104:107]
	v_mfma_f32_16x16x32_bf16 v[92:95], v[166:169], v[190:193], v[92:95]
	v_mfma_f32_16x16x32_bf16 v[88:91], v[174:177], v[190:193], v[88:91]
	v_mfma_f32_16x16x32_bf16 v[76:79], v[166:169], v[202:205], v[76:79]
	v_mfma_f32_16x16x32_bf16 v[72:75], v[174:177], v[202:205], v[72:75]
	v_mfma_f32_16x16x32_bf16 v[68:71], v[166:169], v[220:223], v[68:71]
	v_mfma_f32_16x16x32_bf16 v[64:67], v[174:177], v[220:223], v[64:67]
	v_mfma_f32_16x16x32_bf16 v[108:111], v[170:173], v[186:189], v[108:111]
	v_mfma_f32_16x16x32_bf16 v[104:107], v[178:181], v[186:189], v[104:107]
	v_mfma_f32_16x16x32_bf16 v[92:95], v[170:173], v[198:201], v[92:95]
	v_mfma_f32_16x16x32_bf16 v[88:91], v[178:181], v[198:201], v[88:91]
	v_mfma_f32_16x16x32_bf16 v[76:79], v[170:173], v[216:219], v[76:79]
	v_mfma_f32_16x16x32_bf16 v[72:75], v[178:181], v[216:219], v[72:75]
	v_mfma_f32_16x16x32_bf16 v[68:71], v[170:173], v[224:227], v[68:71]
	v_mfma_f32_16x16x32_bf16 v[64:67], v[178:181], v[224:227], v[64:67]
	s_barrier
; #define PG8_STAGE(bufoff, gbase, voff) do { _Pragma("unroll") for (int _i = 0; _i < 2; ++_i) \
;         __builtin_amdgcn_global_load_lds((const unsigned*)((const char*)(gbase) + (voff)[_i]), (LAS unsigned*)(lds + (bufoff) + ldsw + _i * 8192), 16, 0, 0); } while (0)
; #define PG8_LDA(dst, b, h) do { _Pragma("unroll") for (int m = 0; m < 4; ++m) _Pragma("unroll") for (int k = 0; k < 2; ++k) dst[m][k] = *(const LAS bf16x8*)(lds + PG8_SA(b, h) + aoff + m * 2048 + k * 1024); } while (0)
; #define PG8_MMA(ai, bj, At, Bt) do { __builtin_amdgcn_s_setprio(1); _Pragma("unroll") for (int m = 0; m < 4; ++m) _Pragma("unroll") for (int n = 0; n < 2; ++n) _Pragma("unroll") for (int k = 0; k < 2; ++k) \
;         acc[ai][bj][m][n] = __builtin_amdgcn_mfma_f32_16x16x32_bf16(Bt[n][k], At[m][k], acc[ai][bj][m][n], 0, 0, 0); __builtin_amdgcn_s_setprio(0); } while (0)
; #define PG8_WAIT_V(n) asm volatile("s_waitcnt vmcnt(" #n ")" ::: "memory")
; #define PG8_WAIT_L(n) asm volatile("s_waitcnt lgkmcnt(" #n ")" ::: "memory")
; #define PG8_BAR __builtin_amdgcn_s_barrier()
; #define PG8_SCHED __builtin_amdgcn_sched_barrier(0)
; template <class Epi, bool ALIGN_EPI, bool SP2 = PG8_SP2_DEFAULT>
; __device__ __forceinline__ void gemm_phase(LAS unsigned char* lds, const Gemm g, const StaticOrder& S, const Epi& E) {
;     ...
;         for (int t = 0; t < nt; t += 2) {
;             const bool last = (t == nt - 2);
;             const char* a1 = cA + (size_t)(t + 1) * kstep;
;             const char* a2 = last ? nA : cA + (size_t)(t + 2) * kstep; const char* b2 = last ? nB : cB + (size_t)(t + 2) * kstep;
;             const char* a3 = a2 + kstep; const char* b3 = b2 + kstep;
;     ...
;             PG8_LDA(At, 1, 1); PG8_STAGE(PG8_SB(1, 0), b3, voffB); PG8_STAGE(PG8_SB(1, 1), b3 + hstepB, voffB); PG8_STAGE(PG8_SA(1, 0), a3, voffA);
;             PG8_WAIT_V(8); PG8_WAIT_L(0); PG8_BAR; PG8_MMA(1, 0, At, B0); PG8_MMA(1, 1, At, B1); PG8_BAR; PG8_SCHED;
	s_add_i32 s22, s45, s24
	v_lshl_add_u64 v[206:207], v[206:207], 0, s[4:5]
	s_mov_b32 m0, s22
	ds_read_b128 v[182:185], v149 offset:49152
	ds_read_b128 v[186:189], v149 offset:50176
	ds_read_b128 v[190:193], v149 offset:51200
	ds_read_b128 v[198:201], v149 offset:52224
	ds_read_b128 v[202:205], v149 offset:53248
	ds_read_b128 v[216:219], v149 offset:54272
	ds_read_b128 v[220:223], v149 offset:55296
	ds_read_b128 v[224:227], v149 offset:56320
	global_load_lds_dwordx4 v[206:207], off
	s_add_i32 m0, s22, 0x2000
	s_add_u32 s20, s20, 0x100080
	v_lshl_add_u64 v[206:207], v[210:211], 0, s[4:5]
	s_addc_u32 s21, s21, 0
	s_add_i32 s22, s46, s24
	global_load_lds_dwordx4 v[206:207], off
	v_lshl_add_u64 v[206:207], s[20:21], 0, v[132:133]
	s_mov_b32 m0, s22
	s_nop 0
	global_load_lds_dwordx4 v[206:207], off
	v_lshl_add_u64 v[206:207], s[20:21], 0, v[128:129]
	s_add_i32 m0, s22, 0x2000
	s_nop 0
	global_load_lds_dwordx4 v[206:207], off
	v_lshl_add_u64 v[206:207], v[228:229], 0, s[4:5]
	s_mov_b32 m0, s33
	s_nop 0
	global_load_lds_dwordx4 v[206:207], off
	v_lshl_add_u64 v[206:207], v[230:231], 0, s[4:5]
	s_mov_b32 m0, s34
	s_nop 0
	global_load_lds_dwordx4 v[206:207], off
	s_waitcnt vmcnt(8)
	s_waitcnt lgkmcnt(0)
	s_barrier
	v_mfma_f32_16x16x32_bf16 v[60:63], v[150:153], v[182:185], v[60:63]
	v_mfma_f32_16x16x32_bf16 v[56:59], v[158:161], v[182:185], v[56:59]
	v_mfma_f32_16x16x32_bf16 v[52:55], v[150:153], v[190:193], v[52:55]
	v_mfma_f32_16x16x32_bf16 v[48:51], v[158:161], v[190:193], v[48:51]
	v_mfma_f32_16x16x32_bf16 v[36:39], v[150:153], v[202:205], v[36:39]
	v_mfma_f32_16x16x32_bf16 v[32:35], v[158:161], v[202:205], v[32:35]
	v_mfma_f32_16x16x32_bf16 v[20:23], v[150:153], v[220:223], v[20:23]
	v_mfma_f32_16x16x32_bf16 v[16:19], v[158:161], v[220:223], v[16:19]
	v_mfma_f32_16x16x32_bf16 v[60:63], v[154:157], v[186:189], v[60:63]
	v_mfma_f32_16x16x32_bf16 v[56:59], v[162:165], v[186:189], v[56:59]
	v_mfma_f32_16x16x32_bf16 v[52:55], v[154:157], v[198:201], v[52:55]
	v_mfma_f32_16x16x32_bf16 v[48:51], v[162:165], v[198:201], v[48:51]
	v_mfma_f32_16x16x32_bf16 v[36:39], v[154:157], v[216:219], v[36:39]
	v_mfma_f32_16x16x32_bf16 v[32:35], v[162:165], v[216:219], v[32:35]
	v_mfma_f32_16x16x32_bf16 v[20:23], v[154:157], v[224:227], v[20:23]
	v_mfma_f32_16x16x32_bf16 v[16:19], v[162:165], v[224:227], v[16:19]
	v_mfma_f32_16x16x32_bf16 v[44:47], v[166:169], v[182:185], v[44:47]
	v_mfma_f32_16x16x32_bf16 v[40:43], v[174:177], v[182:185], v[40:43]
	v_mfma_f32_16x16x32_bf16 v[28:31], v[166:169], v[190:193], v[28:31]
	v_mfma_f32_16x16x32_bf16 v[24:27], v[174:177], v[190:193], v[24:27]
	v_mfma_f32_16x16x32_bf16 v[12:15], v[166:169], v[202:205], v[12:15]
	v_mfma_f32_16x16x32_bf16 v[8:11], v[174:177], v[202:205], v[8:11]
	v_mfma_f32_16x16x32_bf16 v[4:7], v[166:169], v[220:223], v[4:7]
	v_mfma_f32_16x16x32_bf16 v[0:3], v[174:177], v[220:223], v[0:3]
	v_mfma_f32_16x16x32_bf16 v[44:47], v[170:173], v[186:189], v[44:47]
	v_mfma_f32_16x16x32_bf16 v[40:43], v[178:181], v[186:189], v[40:43]
	v_mfma_f32_16x16x32_bf16 v[28:31], v[170:173], v[198:201], v[28:31]
	v_mfma_f32_16x16x32_bf16 v[24:27], v[178:181], v[198:201], v[24:27]
	v_mfma_f32_16x16x32_bf16 v[12:15], v[170:173], v[216:219], v[12:15]
	v_mfma_f32_16x16x32_bf16 v[8:11], v[178:181], v[216:219], v[8:11]
	v_mfma_f32_16x16x32_bf16 v[4:7], v[170:173], v[224:227], v[4:7]
	v_mfma_f32_16x16x32_bf16 v[0:3], v[178:181], v[224:227], v[0:3]
	s_barrier
	s_add_i32 s44, s44, 2
	s_add_u32 s18, s18, 0x100
	s_addc_u32 s19, s19, 0
	s_add_u32 s42, s42, 0x100
	s_addc_u32 s43, s43, 0
	s_cmp_gt_u32 s44, 61
	s_cbranch_scc0 .LBB0_250
	s_and_b64 vcc, exec, s[6:7]
	s_cbranch_vccz .LBB0_253
	s_barrier

; #define PG8_STAGE(bufoff, gbase, voff) do { _Pragma("unroll") for (int _i = 0; _i < 2; ++_i) \
;         __builtin_amdgcn_global_load_lds((const unsigned*)((const char*)(gbase) + (voff)[_i]), (LAS unsigned*)(lds + (bufoff) + ldsw + _i * 8192), 16, 0, 0); } while (0)
; #define PG8_LDA(dst, b, h) do { _Pragma("unroll") for (int m = 0; m < 4; ++m) _Pragma("unroll") for (int k = 0; k < 2; ++k) dst[m][k] = *(const LAS bf16x8*)(lds + PG8_SA(b, h) + aoff + m * 2048 + k * 1024); } while (0)
; #define PG8_LDB(dst, b, h) do { _Pragma("unroll") for (int n = 0; n < 2; ++n) _Pragma("unroll") for (int k = 0; k < 2; ++k) dst[n][k] = *(const LAS bf16x8*)(lds + PG8_SB(b, h) + boff + n * 2048 + k * 1024); } while (0)
; #define PG8_MMA(ai, bj, At, Bt) do { __builtin_amdgcn_s_setprio(1); _Pragma("unroll") for (int m = 0; m < 4; ++m) _Pragma("unroll") for (int n = 0; n < 2; ++n) _Pragma("unroll") for (int k = 0; k < 2; ++k) \
;         acc[ai][bj][m][n] = __builtin_amdgcn_mfma_f32_16x16x32_bf16(Bt[n][k], At[m][k], acc[ai][bj][m][n], 0, 0, 0); __builtin_amdgcn_s_setprio(0); } while (0)
; #define PG8_WAIT_V(n) asm volatile("s_waitcnt vmcnt(" #n ")" ::: "memory")
; #define PG8_WAIT_L(n) asm volatile("s_waitcnt lgkmcnt(" #n ")" ::: "memory")
; #define PG8_BAR __builtin_amdgcn_s_barrier()
; #define PG8_SCHED __builtin_amdgcn_sched_barrier(0)
; template <class Epi, bool ALIGN_EPI, bool SP2 = PG8_SP2_DEFAULT>
; __device__ __forceinline__ void gemm_phase(LAS unsigned char* lds, const Gemm g, const StaticOrder& S, const Epi& E) {
;     ...
;             PG8_LDB(B0, 0, 0); PG8_LDB(B1, 0, 1); PG8_SCHED; PG8_LDA(At, 0, 0); PG8_STAGE(PG8_SA(1, 1), a1 + hstepA, voffA);
;             PG8_WAIT_V(8); PG8_WAIT_L(0); PG8_BAR; PG8_MMA(0, 0, At, B0); PG8_MMA(0, 1, At, B1); PG8_BAR; PG8_SCHED;
;             PG8_LDA(At, 0, 1); PG8_STAGE(PG8_SB(0, 0), b2, voffB); PG8_STAGE(PG8_SB(0, 1), b2 + hstepB, voffB); PG8_STAGE(PG8_SA(0, 0), a2, voffA);
.LBB0_428:
	ds_read_b128 v[128:131], v165
	ds_read_b128 v[132:135], v165 offset:1024
	ds_read_b128 v[136:139], v165 offset:2048
	ds_read_b128 v[140:143], v165 offset:3072
	ds_read_b128 v[168:171], v166
	ds_read_b128 v[172:175], v166 offset:1024
	ds_read_b128 v[176:179], v166 offset:2048
	ds_read_b128 v[180:183], v166 offset:3072
	s_add_u32 s24, s22, 0xfffe0080
	s_addc_u32 s25, s23, -1
	s_cmp_eq_u32 s51, 4
	s_cselect_b32 s27, s15, s25
	s_cselect_b32 s26, s47, s24
	s_cselect_b32 s25, s13, s50
	s_cselect_b32 s24, s48, s49
	v_lshl_add_u64 v[160:161], s[22:23], 0, v[152:153]
	s_add_i32 m0, s21, 0xc000
	ds_read_b128 v[184:187], v167
	ds_read_b128 v[188:191], v167 offset:1024
	ds_read_b128 v[198:201], v167 offset:2048
	ds_read_b128 v[202:205], v167 offset:3072
	ds_read_b128 v[216:219], v167 offset:4096
	ds_read_b128 v[220:223], v167 offset:5120
	ds_read_b128 v[224:227], v167 offset:6144
	ds_read_b128 v[228:231], v167 offset:7168
	global_load_lds_dwordx4 v[160:161], off
	v_lshl_add_u64 v[160:161], s[22:23], 0, v[154:155]
	s_add_i32 m0, s21, 0xe000
	s_nop 0
	global_load_lds_dwordx4 v[160:161], off
	s_waitcnt vmcnt(8)
	s_waitcnt lgkmcnt(0)
	s_barrier
	v_mfma_f32_16x16x32_bf16 v[124:127], v[128:131], v[184:187], v[124:127]
	v_mfma_f32_16x16x32_bf16 v[120:123], v[136:139], v[184:187], v[120:123]
	v_mfma_f32_16x16x32_bf16 v[116:119], v[128:131], v[198:201], v[116:119]
	v_mfma_f32_16x16x32_bf16 v[112:115], v[136:139], v[198:201], v[112:115]
	v_mfma_f32_16x16x32_bf16 v[108:111], v[128:131], v[216:219], v[108:111]
	v_mfma_f32_16x16x32_bf16 v[100:103], v[136:139], v[216:219], v[100:103]
	v_mfma_f32_16x16x32_bf16 v[80:83], v[128:131], v[224:227], v[80:83]
	v_mfma_f32_16x16x32_bf16 v[72:75], v[136:139], v[224:227], v[72:75]
	v_mfma_f32_16x16x32_bf16 v[124:127], v[132:135], v[188:191], v[124:127]
	v_mfma_f32_16x16x32_bf16 v[120:123], v[140:143], v[188:191], v[120:123]
	v_mfma_f32_16x16x32_bf16 v[116:119], v[132:135], v[202:205], v[116:119]
	v_mfma_f32_16x16x32_bf16 v[112:115], v[140:143], v[202:205], v[112:115]
	v_mfma_f32_16x16x32_bf16 v[108:111], v[132:135], v[220:223], v[108:111]
	v_mfma_f32_16x16x32_bf16 v[100:103], v[140:143], v[220:223], v[100:103]
	v_mfma_f32_16x16x32_bf16 v[80:83], v[132:135], v[228:231], v[80:83]
	v_mfma_f32_16x16x32_bf16 v[72:75], v[140:143], v[228:231], v[72:75]
	v_mfma_f32_16x16x32_bf16 v[104:107], v[168:171], v[184:187], v[104:107]
	v_mfma_f32_16x16x32_bf16 v[96:99], v[176:179], v[184:187], v[96:99]
	v_mfma_f32_16x16x32_bf16 v[92:95], v[168:171], v[198:201], v[92:95]
	v_mfma_f32_16x16x32_bf16 v[88:91], v[176:179], v[198:201], v[88:91]
	v_mfma_f32_16x16x32_bf16 v[84:87], v[168:171], v[216:219], v[84:87]
	v_mfma_f32_16x16x32_bf16 v[76:79], v[176:179], v[216:219], v[76:79]
	v_mfma_f32_16x16x32_bf16 v[68:71], v[168:171], v[224:227], v[68:71]
	v_mfma_f32_16x16x32_bf16 v[64:67], v[176:179], v[224:227], v[64:67]
	v_mfma_f32_16x16x32_bf16 v[104:107], v[172:175], v[188:191], v[104:107]
	v_mfma_f32_16x16x32_bf16 v[96:99], v[180:183], v[188:191], v[96:99]
	v_mfma_f32_16x16x32_bf16 v[92:95], v[172:175], v[202:205], v[92:95]
	v_mfma_f32_16x16x32_bf16 v[88:91], v[180:183], v[202:205], v[88:91]
	v_mfma_f32_16x16x32_bf16 v[84:87], v[172:175], v[220:223], v[84:87]
	v_mfma_f32_16x16x32_bf16 v[76:79], v[180:183], v[220:223], v[76:79]
	v_mfma_f32_16x16x32_bf16 v[68:71], v[172:175], v[228:231], v[68:71]
	v_mfma_f32_16x16x32_bf16 v[64:67], v[180:183], v[228:231], v[64:67]
	s_barrier
	s_add_i32 s52, s40, s29
	v_lshl_add_u64 v[160:161], s[24:25], 0, v[146:147]
	s_mov_b32 m0, s52
	ds_read_b128 v[184:187], v167 offset:16384
	ds_read_b128 v[188:191], v167 offset:17408
	ds_read_b128 v[198:201], v167 offset:18432
	ds_read_b128 v[202:205], v167 offset:19456
	ds_read_b128 v[216:219], v167 offset:20480
	ds_read_b128 v[220:223], v167 offset:21504
	ds_read_b128 v[224:227], v167 offset:22528
	ds_read_b128 v[228:231], v167 offset:23552
	global_load_lds_dwordx4 v[160:161], off
	s_add_i32 m0, s52, 0x2000
	s_add_u32 s52, s24, 0x20000
	v_lshl_add_u64 v[192:193], s[24:25], 0, v[150:151]
	s_addc_u32 s53, s25, 0
	s_add_i32 s54, s41, s29
	global_load_lds_dwordx4 v[192:193], off
	v_lshl_add_u64 v[206:207], s[52:53], 0, v[146:147]
	s_mov_b32 m0, s54
	v_lshl_add_u64 v[210:211], s[26:27], 0, v[148:149]
	global_load_lds_dwordx4 v[206:207], off
	v_lshl_add_u64 v[206:207], s[52:53], 0, v[150:151]
	s_add_i32 m0, s54, 0x2000
	s_nop 0
	global_load_lds_dwordx4 v[206:207], off
	v_lshl_add_u64 v[206:207], s[26:27], 0, v[144:145]
	s_mov_b32 m0, s21
	s_nop 0
	global_load_lds_dwordx4 v[206:207], off
	s_mov_b32 m0, s30
	s_nop 0
	global_load_lds_dwordx4 v[210:211], off
	s_waitcnt vmcnt(8)
	s_waitcnt lgkmcnt(0)
	s_barrier
; #define PG8_STAGE(bufoff, gbase, voff) do { _Pragma("unroll") for (int _i = 0; _i < 2; ++_i) \
;         __builtin_amdgcn_global_load_lds((const unsigned*)((const char*)(gbase) + (voff)[_i]), (LAS unsigned*)(lds + (bufoff) + ldsw + _i * 8192), 16, 0, 0); } while (0)
; #define PG8_LDA(dst, b, h) do { _Pragma("unroll") for (int m = 0; m < 4; ++m) _Pragma("unroll") for (int k = 0; k < 2; ++k) dst[m][k] = *(const LAS bf16x8*)(lds + PG8_SA(b, h) + aoff + m * 2048 + k * 1024); } while (0)
; #define PG8_LDB(dst, b, h) do { _Pragma("unroll") for (int n = 0; n < 2; ++n) _Pragma("unroll") for (int k = 0; k < 2; ++k) dst[n][k] = *(const LAS bf16x8*)(lds + PG8_SB(b, h) + boff + n * 2048 + k * 1024); } while (0)
; #define PG8_MMA(ai, bj, At, Bt) do { __builtin_amdgcn_s_setprio(1); _Pragma("unroll") for (int m = 0; m < 4; ++m) _Pragma("unroll") for (int n = 0; n < 2; ++n) _Pragma("unroll") for (int k = 0; k < 2; ++k) \
;         acc[ai][bj][m][n] = __builtin_amdgcn_mfma_f32_16x16x32_bf16(Bt[n][k], At[m][k], acc[ai][bj][m][n], 0, 0, 0); __builtin_amdgcn_s_setprio(0); } while (0)
; #define PG8_WAIT_V(n) asm volatile("s_waitcnt vmcnt(" #n ")" ::: "memory")
; #define PG8_WAIT_L(n) asm volatile("s_waitcnt lgkmcnt(" #n ")" ::: "memory")
; #define PG8_BAR __builtin_amdgcn_s_barrier()
; #define PG8_SCHED __builtin_amdgcn_sched_barrier(0)
; template <class Epi, bool ALIGN_EPI, bool SP2 = PG8_SP2_DEFAULT>
; __device__ __forceinline__ void gemm_phase(LAS unsigned char* lds, const Gemm g, const StaticOrder& S, const Epi& E) {
;     ...
;             PG8_WAIT_V(8); PG8_WAIT_L(0); PG8_BAR; PG8_MMA(1, 0, At, B0); PG8_MMA(1, 1, At, B1); PG8_BAR; PG8_SCHED;
;             PG8_LDB(B0, 1, 0); PG8_LDB(B1, 1, 1); PG8_SCHED; PG8_LDA(At, 1, 0); PG8_STAGE(PG8_SA(0, 1), a2 + hstepA, voffA);
;             PG8_WAIT_V(8); PG8_WAIT_L(0); PG8_BAR; PG8_MMA(0, 0, At, B0); PG8_MMA(0, 1, At, B1); PG8_BAR; PG8_SCHED;
	v_mfma_f32_16x16x32_bf16 v[60:63], v[128:131], v[184:187], v[60:63]
	v_mfma_f32_16x16x32_bf16 v[56:59], v[136:139], v[184:187], v[56:59]
	v_mfma_f32_16x16x32_bf16 v[52:55], v[128:131], v[198:201], v[52:55]
	v_mfma_f32_16x16x32_bf16 v[44:47], v[136:139], v[198:201], v[44:47]
	v_mfma_f32_16x16x32_bf16 v[36:39], v[128:131], v[216:219], v[36:39]
	v_mfma_f32_16x16x32_bf16 v[28:31], v[136:139], v[216:219], v[28:31]
	v_mfma_f32_16x16x32_bf16 v[20:23], v[128:131], v[224:227], v[20:23]
	v_mfma_f32_16x16x32_bf16 v[12:15], v[136:139], v[224:227], v[12:15]
	v_mfma_f32_16x16x32_bf16 v[60:63], v[132:135], v[188:191], v[60:63]
	v_mfma_f32_16x16x32_bf16 v[56:59], v[140:143], v[188:191], v[56:59]
	v_mfma_f32_16x16x32_bf16 v[52:55], v[132:135], v[202:205], v[52:55]
	v_mfma_f32_16x16x32_bf16 v[44:47], v[140:143], v[202:205], v[44:47]
	v_mfma_f32_16x16x32_bf16 v[36:39], v[132:135], v[220:223], v[36:39]
	v_mfma_f32_16x16x32_bf16 v[28:31], v[140:143], v[220:223], v[28:31]
	v_mfma_f32_16x16x32_bf16 v[20:23], v[132:135], v[228:231], v[20:23]
	v_mfma_f32_16x16x32_bf16 v[12:15], v[140:143], v[228:231], v[12:15]
	v_mfma_f32_16x16x32_bf16 v[48:51], v[168:171], v[184:187], v[48:51]
	v_mfma_f32_16x16x32_bf16 v[40:43], v[176:179], v[184:187], v[40:43]
	v_mfma_f32_16x16x32_bf16 v[32:35], v[168:171], v[198:201], v[32:35]
	v_mfma_f32_16x16x32_bf16 v[24:27], v[176:179], v[198:201], v[24:27]
	v_mfma_f32_16x16x32_bf16 v[16:19], v[168:171], v[216:219], v[16:19]
	v_mfma_f32_16x16x32_bf16 v[8:11], v[176:179], v[216:219], v[8:11]
	v_mfma_f32_16x16x32_bf16 v[4:7], v[168:171], v[224:227], v[4:7]
	v_mfma_f32_16x16x32_bf16 v[0:3], v[176:179], v[224:227], v[0:3]
	v_mfma_f32_16x16x32_bf16 v[48:51], v[172:175], v[188:191], v[48:51]
	v_mfma_f32_16x16x32_bf16 v[40:43], v[180:183], v[188:191], v[40:43]
	v_mfma_f32_16x16x32_bf16 v[32:35], v[172:175], v[202:205], v[32:35]
	v_mfma_f32_16x16x32_bf16 v[24:27], v[180:183], v[202:205], v[24:27]
	v_mfma_f32_16x16x32_bf16 v[16:19], v[172:175], v[220:223], v[16:19]
	v_mfma_f32_16x16x32_bf16 v[8:11], v[180:183], v[220:223], v[8:11]
	v_mfma_f32_16x16x32_bf16 v[4:7], v[172:175], v[228:231], v[4:7]
	v_mfma_f32_16x16x32_bf16 v[0:3], v[180:183], v[228:231], v[0:3]
	s_barrier
	s_add_i32 s52, 0, 0x18000
	s_add_i32 s53, 0, 0x1c000
	v_add_u32_e32 v140, s52, v163
	v_add_u32_e32 v180, s53, v163
	ds_read_b128 v[128:131], v140
	ds_read_b128 v[132:135], v140 offset:1024
	ds_read_b128 v[136:139], v140 offset:2048
	ds_read_b128 v[140:143], v140 offset:3072
	ds_read_b128 v[168:171], v180
	ds_read_b128 v[172:175], v180 offset:1024
	ds_read_b128 v[176:179], v180 offset:2048
	ds_read_b128 v[180:183], v180 offset:3072
	s_add_u32 s26, s26, 0x20000
	s_addc_u32 s27, s27, 0
	s_mov_b32 m0, s31
	v_lshl_add_u64 v[232:233], s[26:27], 0, v[144:145]
	ds_read_b128 v[184:187], v167 offset:32768
	ds_read_b128 v[188:191], v167 offset:33792
	ds_read_b128 v[198:201], v167 offset:34816
	ds_read_b128 v[202:205], v167 offset:35840
	ds_read_b128 v[216:219], v167 offset:36864
	ds_read_b128 v[220:223], v167 offset:37888
	ds_read_b128 v[224:227], v167 offset:38912
	ds_read_b128 v[228:231], v167 offset:39936
	global_load_lds_dwordx4 v[232:233], off
	v_lshl_add_u64 v[232:233], s[26:27], 0, v[148:149]
	s_mov_b32 m0, s34
	s_nop 0
	global_load_lds_dwordx4 v[232:233], off
	s_waitcnt vmcnt(8)
	s_waitcnt lgkmcnt(0)
	s_barrier
	v_mfma_f32_16x16x32_bf16 v[124:127], v[128:131], v[184:187], v[124:127]
	v_mfma_f32_16x16x32_bf16 v[120:123], v[136:139], v[184:187], v[120:123]
	v_mfma_f32_16x16x32_bf16 v[116:119], v[128:131], v[198:201], v[116:119]
	v_mfma_f32_16x16x32_bf16 v[112:115], v[136:139], v[198:201], v[112:115]
	v_mfma_f32_16x16x32_bf16 v[108:111], v[128:131], v[216:219], v[108:111]
	v_mfma_f32_16x16x32_bf16 v[100:103], v[136:139], v[216:219], v[100:103]
	v_mfma_f32_16x16x32_bf16 v[80:83], v[128:131], v[224:227], v[80:83]
	v_mfma_f32_16x16x32_bf16 v[72:75], v[136:139], v[224:227], v[72:75]
	v_mfma_f32_16x16x32_bf16 v[124:127], v[132:135], v[188:191], v[124:127]
	v_mfma_f32_16x16x32_bf16 v[120:123], v[140:143], v[188:191], v[120:123]
	v_mfma_f32_16x16x32_bf16 v[116:119], v[132:135], v[202:205], v[116:119]
	v_mfma_f32_16x16x32_bf16 v[112:115], v[140:143], v[202:205], v[112:115]
	v_mfma_f32_16x16x32_bf16 v[108:111], v[132:135], v[220:223], v[108:111]
	v_mfma_f32_16x16x32_bf16 v[100:103], v[140:143], v[220:223], v[100:103]
	v_mfma_f32_16x16x32_bf16 v[80:83], v[132:135], v[228:231], v[80:83]
	v_mfma_f32_16x16x32_bf16 v[72:75], v[140:143], v[228:231], v[72:75]
	v_mfma_f32_16x16x32_bf16 v[104:107], v[168:171], v[184:187], v[104:107]
	v_mfma_f32_16x16x32_bf16 v[96:99], v[176:179], v[184:187], v[96:99]
	v_mfma_f32_16x16x32_bf16 v[92:95], v[168:171], v[198:201], v[92:95]
	v_mfma_f32_16x16x32_bf16 v[88:91], v[176:179], v[198:201], v[88:91]
	v_mfma_f32_16x16x32_bf16 v[84:87], v[168:171], v[216:219], v[84:87]
	v_mfma_f32_16x16x32_bf16 v[76:79], v[176:179], v[216:219], v[76:79]
	v_mfma_f32_16x16x32_bf16 v[68:71], v[168:171], v[224:227], v[68:71]
	v_mfma_f32_16x16x32_bf16 v[64:67], v[176:179], v[224:227], v[64:67]
	v_mfma_f32_16x16x32_bf16 v[104:107], v[172:175], v[188:191], v[104:107]
	v_mfma_f32_16x16x32_bf16 v[96:99], v[180:183], v[188:191], v[96:99]
	v_mfma_f32_16x16x32_bf16 v[92:95], v[172:175], v[202:205], v[92:95]
	v_mfma_f32_16x16x32_bf16 v[88:91], v[180:183], v[202:205], v[88:91]
	v_mfma_f32_16x16x32_bf16 v[84:87], v[172:175], v[220:223], v[84:87]
	v_mfma_f32_16x16x32_bf16 v[76:79], v[180:183], v[220:223], v[76:79]
	v_mfma_f32_16x16x32_bf16 v[68:71], v[172:175], v[228:231], v[68:71]
	v_mfma_f32_16x16x32_bf16 v[64:67], v[180:183], v[228:231], v[64:67]
	s_barrier
; #define PG8_STAGE(bufoff, gbase, voff) do { _Pragma("unroll") for (int _i = 0; _i < 2; ++_i) \
;         __builtin_amdgcn_global_load_lds((const unsigned*)((const char*)(gbase) + (voff)[_i]), (LAS unsigned*)(lds + (bufoff) + ldsw + _i * 8192), 16, 0, 0); } while (0)
; #define PG8_LDA(dst, b, h) do { _Pragma("unroll") for (int m = 0; m < 4; ++m) _Pragma("unroll") for (int k = 0; k < 2; ++k) dst[m][k] = *(const LAS bf16x8*)(lds + PG8_SA(b, h) + aoff + m * 2048 + k * 1024); } while (0)
; #define PG8_MMA(ai, bj, At, Bt) do { __builtin_amdgcn_s_setprio(1); _Pragma("unroll") for (int m = 0; m < 4; ++m) _Pragma("unroll") for (int n = 0; n < 2; ++n) _Pragma("unroll") for (int k = 0; k < 2; ++k) \
;         acc[ai][bj][m][n] = __builtin_amdgcn_mfma_f32_16x16x32_bf16(Bt[n][k], At[m][k], acc[ai][bj][m][n], 0, 0, 0); __builtin_amdgcn_s_setprio(0); } while (0)
; #define PG8_WAIT_V(n) asm volatile("s_waitcnt vmcnt(" #n ")" ::: "memory")
; #define PG8_WAIT_L(n) asm volatile("s_waitcnt lgkmcnt(" #n ")" ::: "memory")
; #define PG8_BAR __builtin_amdgcn_s_barrier()
; #define PG8_SCHED __builtin_amdgcn_sched_barrier(0)
; template <class Epi, bool ALIGN_EPI, bool SP2 = PG8_SP2_DEFAULT>
; __device__ __forceinline__ void gemm_phase(LAS unsigned char* lds, const Gemm g, const StaticOrder& S, const Epi& E) {
;     ...
;             PG8_LDA(At, 1, 1); PG8_STAGE(PG8_SB(1, 0), b3, voffB); PG8_STAGE(PG8_SB(1, 1), b3 + hstepB, voffB); PG8_STAGE(PG8_SA(1, 0), a3, voffA);
;             PG8_WAIT_V(8); PG8_WAIT_L(0); PG8_BAR; PG8_MMA(1, 0, At, B0); PG8_MMA(1, 1, At, B1); PG8_BAR; PG8_SCHED;
;     ...
;         if constexpr (ALIGN_EPI) { if (wr == 0) PG8_BAR; }
	s_add_i32 s26, s52, s29
	v_lshl_add_u64 v[160:161], v[160:161], 0, s[4:5]
	s_mov_b32 m0, s26
	ds_read_b128 v[184:187], v167 offset:49152
	ds_read_b128 v[188:191], v167 offset:50176
	ds_read_b128 v[198:201], v167 offset:51200
	ds_read_b128 v[202:205], v167 offset:52224
	ds_read_b128 v[216:219], v167 offset:53248
	ds_read_b128 v[220:223], v167 offset:54272
	ds_read_b128 v[224:227], v167 offset:55296
	ds_read_b128 v[228:231], v167 offset:56320
	global_load_lds_dwordx4 v[160:161], off
	s_add_i32 m0, s26, 0x2000
	s_add_u32 s24, s24, 0x20080
	v_lshl_add_u64 v[160:161], v[192:193], 0, s[4:5]
	s_addc_u32 s25, s25, 0
	s_add_i32 s26, s53, s29
	global_load_lds_dwordx4 v[160:161], off
	v_lshl_add_u64 v[160:161], s[24:25], 0, v[146:147]
	s_mov_b32 m0, s26
	s_nop 0
	global_load_lds_dwordx4 v[160:161], off
	v_lshl_add_u64 v[160:161], s[24:25], 0, v[150:151]
	s_add_i32 m0, s26, 0x2000
	s_nop 0
	global_load_lds_dwordx4 v[160:161], off
	v_lshl_add_u64 v[160:161], v[206:207], 0, s[4:5]
	s_mov_b32 m0, s36
	s_nop 0
	global_load_lds_dwordx4 v[160:161], off
	v_lshl_add_u64 v[160:161], v[210:211], 0, s[4:5]
	s_mov_b32 m0, s37
	s_nop 0
	global_load_lds_dwordx4 v[160:161], off
	s_waitcnt vmcnt(8)
	s_waitcnt lgkmcnt(0)
	s_barrier
	v_mfma_f32_16x16x32_bf16 v[60:63], v[128:131], v[184:187], v[60:63]
	v_mfma_f32_16x16x32_bf16 v[56:59], v[136:139], v[184:187], v[56:59]
	v_mfma_f32_16x16x32_bf16 v[52:55], v[128:131], v[198:201], v[52:55]
	v_mfma_f32_16x16x32_bf16 v[44:47], v[136:139], v[198:201], v[44:47]
	v_mfma_f32_16x16x32_bf16 v[36:39], v[128:131], v[216:219], v[36:39]
	v_mfma_f32_16x16x32_bf16 v[28:31], v[136:139], v[216:219], v[28:31]
	v_mfma_f32_16x16x32_bf16 v[20:23], v[128:131], v[224:227], v[20:23]
	v_mfma_f32_16x16x32_bf16 v[12:15], v[136:139], v[224:227], v[12:15]
	v_mfma_f32_16x16x32_bf16 v[60:63], v[132:135], v[188:191], v[60:63]
	v_mfma_f32_16x16x32_bf16 v[56:59], v[140:143], v[188:191], v[56:59]
	v_mfma_f32_16x16x32_bf16 v[52:55], v[132:135], v[202:205], v[52:55]
	v_mfma_f32_16x16x32_bf16 v[44:47], v[140:143], v[202:205], v[44:47]
	v_mfma_f32_16x16x32_bf16 v[36:39], v[132:135], v[220:223], v[36:39]
	v_mfma_f32_16x16x32_bf16 v[28:31], v[140:143], v[220:223], v[28:31]
	v_mfma_f32_16x16x32_bf16 v[20:23], v[132:135], v[228:231], v[20:23]
	v_mfma_f32_16x16x32_bf16 v[12:15], v[140:143], v[228:231], v[12:15]
	v_mfma_f32_16x16x32_bf16 v[48:51], v[168:171], v[184:187], v[48:51]
	v_mfma_f32_16x16x32_bf16 v[40:43], v[176:179], v[184:187], v[40:43]
	v_mfma_f32_16x16x32_bf16 v[32:35], v[168:171], v[198:201], v[32:35]
	v_mfma_f32_16x16x32_bf16 v[24:27], v[176:179], v[198:201], v[24:27]
	v_mfma_f32_16x16x32_bf16 v[16:19], v[168:171], v[216:219], v[16:19]
	v_mfma_f32_16x16x32_bf16 v[8:11], v[176:179], v[216:219], v[8:11]
	v_mfma_f32_16x16x32_bf16 v[4:7], v[168:171], v[224:227], v[4:7]
	v_mfma_f32_16x16x32_bf16 v[0:3], v[176:179], v[224:227], v[0:3]
	v_mfma_f32_16x16x32_bf16 v[48:51], v[172:175], v[188:191], v[48:51]
	v_mfma_f32_16x16x32_bf16 v[40:43], v[180:183], v[188:191], v[40:43]
	v_mfma_f32_16x16x32_bf16 v[32:35], v[172:175], v[202:205], v[32:35]
	v_mfma_f32_16x16x32_bf16 v[24:27], v[180:183], v[202:205], v[24:27]
	v_mfma_f32_16x16x32_bf16 v[16:19], v[172:175], v[220:223], v[16:19]
	v_mfma_f32_16x16x32_bf16 v[8:11], v[180:183], v[220:223], v[8:11]
	v_mfma_f32_16x16x32_bf16 v[4:7], v[172:175], v[228:231], v[4:7]
	v_mfma_f32_16x16x32_bf16 v[0:3], v[180:183], v[228:231], v[0:3]
	s_barrier
	s_add_i32 s51, s51, 2
	s_add_u32 s22, s22, 0x100
	s_addc_u32 s23, s23, 0
	s_add_u32 s49, s49, 0x100
	s_addc_u32 s50, s50, 0
	s_cmp_gt_u32 s51, 5
	s_cbranch_scc0 .LBB0_428
	s_and_b64 vcc, exec, s[6:7]
	s_cbranch_vccz .LBB0_431
	s_barrier

; #define PG8_STAGE(bufoff, gbase, voff) do { _Pragma("unroll") for (int _i = 0; _i < 2; ++_i) \
;         __builtin_amdgcn_global_load_lds((const unsigned*)((const char*)(gbase) + (voff)[_i]), (LAS unsigned*)(lds + (bufoff) + ldsw + _i * 8192), 16, 0, 0); } while (0)
; #define PG8_LDA(dst, b, h) do { _Pragma("unroll") for (int m = 0; m < 4; ++m) _Pragma("unroll") for (int k = 0; k < 2; ++k) dst[m][k] = *(const LAS bf16x8*)(lds + PG8_SA(b, h) + aoff + m * 2048 + k * 1024); } while (0)
; #define PG8_LDB(dst, b, h) do { _Pragma("unroll") for (int n = 0; n < 2; ++n) _Pragma("unroll") for (int k = 0; k < 2; ++k) dst[n][k] = *(const LAS bf16x8*)(lds + PG8_SB(b, h) + boff + n * 2048 + k * 1024); } while (0)
; #define PG8_MMA(ai, bj, At, Bt) do { __builtin_amdgcn_s_setprio(1); _Pragma("unroll") for (int m = 0; m < 4; ++m) _Pragma("unroll") for (int n = 0; n < 2; ++n) _Pragma("unroll") for (int k = 0; k < 2; ++k) \
;         acc[ai][bj][m][n] = __builtin_amdgcn_mfma_f32_16x16x32_bf16(Bt[n][k], At[m][k], acc[ai][bj][m][n], 0, 0, 0); __builtin_amdgcn_s_setprio(0); } while (0)
; #define PG8_WAIT_V(n) asm volatile("s_waitcnt vmcnt(" #n ")" ::: "memory")
; #define PG8_WAIT_L(n) asm volatile("s_waitcnt lgkmcnt(" #n ")" ::: "memory")
; #define PG8_BAR __builtin_amdgcn_s_barrier()
; #define PG8_SCHED __builtin_amdgcn_sched_barrier(0)
; template <class Epi, bool ALIGN_EPI, bool SP2 = PG8_SP2_DEFAULT>
; __device__ __forceinline__ void gemm_phase(LAS unsigned char* lds, const Gemm g, const StaticOrder& S, const Epi& E) {
;     ...
;             PG8_LDB(B0, 0, 0); PG8_LDB(B1, 0, 1); PG8_SCHED; PG8_LDA(At, 0, 0); PG8_STAGE(PG8_SA(1, 1), a1 + hstepA, voffA);
;             PG8_WAIT_V(8); PG8_WAIT_L(0); PG8_BAR; PG8_MMA(0, 0, At, B0); PG8_MMA(0, 1, At, B1); PG8_BAR; PG8_SCHED;
;             PG8_LDA(At, 0, 1); PG8_STAGE(PG8_SB(0, 0), b2, voffB); PG8_STAGE(PG8_SB(0, 1), b2 + hstepB, voffB); PG8_STAGE(PG8_SA(0, 0), a2, voffA);
.LBB0_506:
	ds_read_b128 v[144:147], v151
	ds_read_b128 v[156:159], v151 offset:1024
	ds_read_b128 v[160:163], v151 offset:2048
	ds_read_b128 v[164:167], v151 offset:3072
	ds_read_b128 v[168:171], v152
	ds_read_b128 v[172:175], v152 offset:1024
	ds_read_b128 v[176:179], v152 offset:2048
	ds_read_b128 v[180:183], v152 offset:3072
	s_add_u32 s28, s26, 0xfff00080
	s_addc_u32 s29, s27, -1
	s_cmp_eq_u32 s50, 60
	s_cselect_b32 s31, s19, s29
	s_cselect_b32 s30, s25, s28
	s_cselect_b32 s29, s3, s49
	s_cselect_b32 s28, s47, s48
	v_lshl_add_u64 v[192:193], s[26:27], 0, v[136:137]
	s_add_i32 m0, s34, 0xc000
	ds_read_b128 v[184:187], v153
	ds_read_b128 v[188:191], v153 offset:1024
	ds_read_b128 v[198:201], v153 offset:2048
	ds_read_b128 v[202:205], v153 offset:3072
	ds_read_b128 v[216:219], v153 offset:4096
	ds_read_b128 v[220:223], v153 offset:5120
	ds_read_b128 v[224:227], v153 offset:6144
	ds_read_b128 v[228:231], v153 offset:7168
	global_load_lds_dwordx4 v[192:193], off
	v_lshl_add_u64 v[192:193], s[26:27], 0, v[138:139]
	s_add_i32 m0, s34, 0xe000
	s_nop 0
	global_load_lds_dwordx4 v[192:193], off
	s_waitcnt vmcnt(8)
	s_waitcnt lgkmcnt(0)
	s_barrier
	v_mfma_f32_16x16x32_bf16 v[124:127], v[144:147], v[184:187], v[124:127]
	v_mfma_f32_16x16x32_bf16 v[120:123], v[160:163], v[184:187], v[120:123]
	v_mfma_f32_16x16x32_bf16 v[108:111], v[144:147], v[198:201], v[108:111]
	v_mfma_f32_16x16x32_bf16 v[104:107], v[160:163], v[198:201], v[104:107]
	v_mfma_f32_16x16x32_bf16 v[92:95], v[144:147], v[216:219], v[92:95]
	v_mfma_f32_16x16x32_bf16 v[88:91], v[160:163], v[216:219], v[88:91]
	v_mfma_f32_16x16x32_bf16 v[76:79], v[144:147], v[224:227], v[76:79]
	v_mfma_f32_16x16x32_bf16 v[72:75], v[160:163], v[224:227], v[72:75]
	v_mfma_f32_16x16x32_bf16 v[124:127], v[156:159], v[188:191], v[124:127]
	v_mfma_f32_16x16x32_bf16 v[120:123], v[164:167], v[188:191], v[120:123]
	v_mfma_f32_16x16x32_bf16 v[108:111], v[156:159], v[202:205], v[108:111]
	v_mfma_f32_16x16x32_bf16 v[104:107], v[164:167], v[202:205], v[104:107]
	v_mfma_f32_16x16x32_bf16 v[92:95], v[156:159], v[220:223], v[92:95]
	v_mfma_f32_16x16x32_bf16 v[88:91], v[164:167], v[220:223], v[88:91]
	v_mfma_f32_16x16x32_bf16 v[76:79], v[156:159], v[228:231], v[76:79]
	v_mfma_f32_16x16x32_bf16 v[72:75], v[164:167], v[228:231], v[72:75]
	v_mfma_f32_16x16x32_bf16 v[116:119], v[168:171], v[184:187], v[116:119]
	v_mfma_f32_16x16x32_bf16 v[112:115], v[176:179], v[184:187], v[112:115]
	v_mfma_f32_16x16x32_bf16 v[100:103], v[168:171], v[198:201], v[100:103]
	v_mfma_f32_16x16x32_bf16 v[96:99], v[176:179], v[198:201], v[96:99]
	v_mfma_f32_16x16x32_bf16 v[84:87], v[168:171], v[216:219], v[84:87]
	v_mfma_f32_16x16x32_bf16 v[80:83], v[176:179], v[216:219], v[80:83]
	v_mfma_f32_16x16x32_bf16 v[68:71], v[168:171], v[224:227], v[68:71]
	v_mfma_f32_16x16x32_bf16 v[64:67], v[176:179], v[224:227], v[64:67]
	v_mfma_f32_16x16x32_bf16 v[116:119], v[172:175], v[188:191], v[116:119]
	v_mfma_f32_16x16x32_bf16 v[112:115], v[180:183], v[188:191], v[112:115]
	v_mfma_f32_16x16x32_bf16 v[100:103], v[172:175], v[202:205], v[100:103]
	v_mfma_f32_16x16x32_bf16 v[96:99], v[180:183], v[202:205], v[96:99]
	v_mfma_f32_16x16x32_bf16 v[84:87], v[172:175], v[220:223], v[84:87]
	v_mfma_f32_16x16x32_bf16 v[80:83], v[180:183], v[220:223], v[80:83]
	v_mfma_f32_16x16x32_bf16 v[68:71], v[172:175], v[228:231], v[68:71]
	v_mfma_f32_16x16x32_bf16 v[64:67], v[180:183], v[228:231], v[64:67]
	s_barrier
	s_add_i32 s51, s44, s33
	v_lshl_add_u64 v[192:193], s[28:29], 0, v[130:131]
	s_mov_b32 m0, s51
	ds_read_b128 v[184:187], v153 offset:16384
	ds_read_b128 v[188:191], v153 offset:17408
	ds_read_b128 v[198:201], v153 offset:18432
	ds_read_b128 v[202:205], v153 offset:19456
	ds_read_b128 v[216:219], v153 offset:20480
	ds_read_b128 v[220:223], v153 offset:21504
	ds_read_b128 v[224:227], v153 offset:22528
	ds_read_b128 v[228:231], v153 offset:23552
	global_load_lds_dwordx4 v[192:193], off
	s_add_i32 m0, s51, 0x2000
	s_add_u32 s52, s28, 0x100000
	v_lshl_add_u64 v[206:207], s[28:29], 0, v[134:135]
	s_addc_u32 s53, s29, 0
	s_add_i32 s51, s45, s33
	global_load_lds_dwordx4 v[206:207], off
	v_lshl_add_u64 v[210:211], s[52:53], 0, v[130:131]
	s_mov_b32 m0, s51
	v_lshl_add_u64 v[232:233], s[30:31], 0, v[132:133]
	global_load_lds_dwordx4 v[210:211], off
	v_lshl_add_u64 v[210:211], s[52:53], 0, v[134:135]
	s_add_i32 m0, s51, 0x2000
	s_nop 0
	global_load_lds_dwordx4 v[210:211], off
	v_lshl_add_u64 v[210:211], s[30:31], 0, v[128:129]
	s_mov_b32 m0, s34
	s_nop 0
	global_load_lds_dwordx4 v[210:211], off
	s_mov_b32 m0, s35
	s_nop 0
	global_load_lds_dwordx4 v[232:233], off
	s_waitcnt vmcnt(8)
	s_waitcnt lgkmcnt(0)
	s_barrier
; #define PG8_STAGE(bufoff, gbase, voff) do { _Pragma("unroll") for (int _i = 0; _i < 2; ++_i) \
;         __builtin_amdgcn_global_load_lds((const unsigned*)((const char*)(gbase) + (voff)[_i]), (LAS unsigned*)(lds + (bufoff) + ldsw + _i * 8192), 16, 0, 0); } while (0)
; #define PG8_LDA(dst, b, h) do { _Pragma("unroll") for (int m = 0; m < 4; ++m) _Pragma("unroll") for (int k = 0; k < 2; ++k) dst[m][k] = *(const LAS bf16x8*)(lds + PG8_SA(b, h) + aoff + m * 2048 + k * 1024); } while (0)
; #define PG8_LDB(dst, b, h) do { _Pragma("unroll") for (int n = 0; n < 2; ++n) _Pragma("unroll") for (int k = 0; k < 2; ++k) dst[n][k] = *(const LAS bf16x8*)(lds + PG8_SB(b, h) + boff + n * 2048 + k * 1024); } while (0)
; #define PG8_MMA(ai, bj, At, Bt) do { __builtin_amdgcn_s_setprio(1); _Pragma("unroll") for (int m = 0; m < 4; ++m) _Pragma("unroll") for (int n = 0; n < 2; ++n) _Pragma("unroll") for (int k = 0; k < 2; ++k) \
;         acc[ai][bj][m][n] = __builtin_amdgcn_mfma_f32_16x16x32_bf16(Bt[n][k], At[m][k], acc[ai][bj][m][n], 0, 0, 0); __builtin_amdgcn_s_setprio(0); } while (0)
; #define PG8_WAIT_V(n) asm volatile("s_waitcnt vmcnt(" #n ")" ::: "memory")
; #define PG8_WAIT_L(n) asm volatile("s_waitcnt lgkmcnt(" #n ")" ::: "memory")
; #define PG8_BAR __builtin_amdgcn_s_barrier()
; #define PG8_SCHED __builtin_amdgcn_sched_barrier(0)
; template <class Epi, bool ALIGN_EPI, bool SP2 = PG8_SP2_DEFAULT>
; __device__ __forceinline__ void gemm_phase(LAS unsigned char* lds, const Gemm g, const StaticOrder& S, const Epi& E) {
;     ...
;             PG8_WAIT_V(8); PG8_WAIT_L(0); PG8_BAR; PG8_MMA(1, 0, At, B0); PG8_MMA(1, 1, At, B1); PG8_BAR; PG8_SCHED;
;             PG8_LDB(B0, 1, 0); PG8_LDB(B1, 1, 1); PG8_SCHED; PG8_LDA(At, 1, 0); PG8_STAGE(PG8_SA(0, 1), a2 + hstepA, voffA);
;             PG8_WAIT_V(8); PG8_WAIT_L(0); PG8_BAR; PG8_MMA(0, 0, At, B0); PG8_MMA(0, 1, At, B1); PG8_BAR; PG8_SCHED;
	v_mfma_f32_16x16x32_bf16 v[60:63], v[144:147], v[184:187], v[60:63]
	v_mfma_f32_16x16x32_bf16 v[56:59], v[160:163], v[184:187], v[56:59]
	v_mfma_f32_16x16x32_bf16 v[44:47], v[144:147], v[198:201], v[44:47]
	v_mfma_f32_16x16x32_bf16 v[40:43], v[160:163], v[198:201], v[40:43]
	v_mfma_f32_16x16x32_bf16 v[28:31], v[144:147], v[216:219], v[28:31]
	v_mfma_f32_16x16x32_bf16 v[24:27], v[160:163], v[216:219], v[24:27]
	v_mfma_f32_16x16x32_bf16 v[12:15], v[144:147], v[224:227], v[12:15]
	v_mfma_f32_16x16x32_bf16 v[8:11], v[160:163], v[224:227], v[8:11]
	v_mfma_f32_16x16x32_bf16 v[60:63], v[156:159], v[188:191], v[60:63]
	v_mfma_f32_16x16x32_bf16 v[56:59], v[164:167], v[188:191], v[56:59]
	v_mfma_f32_16x16x32_bf16 v[44:47], v[156:159], v[202:205], v[44:47]
	v_mfma_f32_16x16x32_bf16 v[40:43], v[164:167], v[202:205], v[40:43]
	v_mfma_f32_16x16x32_bf16 v[28:31], v[156:159], v[220:223], v[28:31]
	v_mfma_f32_16x16x32_bf16 v[24:27], v[164:167], v[220:223], v[24:27]
	v_mfma_f32_16x16x32_bf16 v[12:15], v[156:159], v[228:231], v[12:15]
	v_mfma_f32_16x16x32_bf16 v[8:11], v[164:167], v[228:231], v[8:11]
	v_mfma_f32_16x16x32_bf16 v[52:55], v[168:171], v[184:187], v[52:55]
	v_mfma_f32_16x16x32_bf16 v[48:51], v[176:179], v[184:187], v[48:51]
	v_mfma_f32_16x16x32_bf16 v[36:39], v[168:171], v[198:201], v[36:39]
	v_mfma_f32_16x16x32_bf16 v[32:35], v[176:179], v[198:201], v[32:35]
	v_mfma_f32_16x16x32_bf16 v[20:23], v[168:171], v[216:219], v[20:23]
	v_mfma_f32_16x16x32_bf16 v[16:19], v[176:179], v[216:219], v[16:19]
	v_mfma_f32_16x16x32_bf16 v[4:7], v[168:171], v[224:227], v[4:7]
	v_mfma_f32_16x16x32_bf16 v[0:3], v[176:179], v[224:227], v[0:3]
	v_mfma_f32_16x16x32_bf16 v[52:55], v[172:175], v[188:191], v[52:55]
	v_mfma_f32_16x16x32_bf16 v[48:51], v[180:183], v[188:191], v[48:51]
	v_mfma_f32_16x16x32_bf16 v[36:39], v[172:175], v[202:205], v[36:39]
	v_mfma_f32_16x16x32_bf16 v[32:35], v[180:183], v[202:205], v[32:35]
	v_mfma_f32_16x16x32_bf16 v[20:23], v[172:175], v[220:223], v[20:23]
	v_mfma_f32_16x16x32_bf16 v[16:19], v[180:183], v[220:223], v[16:19]
	v_mfma_f32_16x16x32_bf16 v[4:7], v[172:175], v[228:231], v[4:7]
	v_mfma_f32_16x16x32_bf16 v[0:3], v[180:183], v[228:231], v[0:3]
	s_barrier
	s_add_i32 s51, 0, 0x18000
	v_add_u32_e32 v155, s51, v149
	s_add_i32 s52, 0, 0x1c000
	ds_read_b128 v[144:147], v155
	ds_read_b128 v[156:159], v155 offset:1024
	ds_read_b128 v[160:163], v155 offset:2048
	ds_read_b128 v[164:167], v155 offset:3072
	v_add_u32_e32 v155, s52, v149
	ds_read_b128 v[168:171], v155
	ds_read_b128 v[172:175], v155 offset:1024
	ds_read_b128 v[176:179], v155 offset:2048
	ds_read_b128 v[180:183], v155 offset:3072
	s_add_u32 s30, s30, 0x100000
	s_addc_u32 s31, s31, 0
	s_mov_b32 m0, s36
	v_lshl_add_u64 v[234:235], s[30:31], 0, v[128:129]
	ds_read_b128 v[184:187], v153 offset:32768
	ds_read_b128 v[188:191], v153 offset:33792
	ds_read_b128 v[198:201], v153 offset:34816
	ds_read_b128 v[202:205], v153 offset:35840
	ds_read_b128 v[216:219], v153 offset:36864
	ds_read_b128 v[220:223], v153 offset:37888
	ds_read_b128 v[224:227], v153 offset:38912
	ds_read_b128 v[228:231], v153 offset:39936
	global_load_lds_dwordx4 v[234:235], off
	v_lshl_add_u64 v[234:235], s[30:31], 0, v[132:133]
	s_mov_b32 m0, s37
	s_nop 0
	global_load_lds_dwordx4 v[234:235], off
	s_waitcnt vmcnt(8)
	s_waitcnt lgkmcnt(0)
	s_barrier
	v_mfma_f32_16x16x32_bf16 v[124:127], v[144:147], v[184:187], v[124:127]
	v_mfma_f32_16x16x32_bf16 v[120:123], v[160:163], v[184:187], v[120:123]
	v_mfma_f32_16x16x32_bf16 v[108:111], v[144:147], v[198:201], v[108:111]
	v_mfma_f32_16x16x32_bf16 v[104:107], v[160:163], v[198:201], v[104:107]
	v_mfma_f32_16x16x32_bf16 v[92:95], v[144:147], v[216:219], v[92:95]
	v_mfma_f32_16x16x32_bf16 v[88:91], v[160:163], v[216:219], v[88:91]
	v_mfma_f32_16x16x32_bf16 v[76:79], v[144:147], v[224:227], v[76:79]
	v_mfma_f32_16x16x32_bf16 v[72:75], v[160:163], v[224:227], v[72:75]
	v_mfma_f32_16x16x32_bf16 v[124:127], v[156:159], v[188:191], v[124:127]
	v_mfma_f32_16x16x32_bf16 v[120:123], v[164:167], v[188:191], v[120:123]
	v_mfma_f32_16x16x32_bf16 v[108:111], v[156:159], v[202:205], v[108:111]
	v_mfma_f32_16x16x32_bf16 v[104:107], v[164:167], v[202:205], v[104:107]
	v_mfma_f32_16x16x32_bf16 v[92:95], v[156:159], v[220:223], v[92:95]
	v_mfma_f32_16x16x32_bf16 v[88:91], v[164:167], v[220:223], v[88:91]
	v_mfma_f32_16x16x32_bf16 v[76:79], v[156:159], v[228:231], v[76:79]
	v_mfma_f32_16x16x32_bf16 v[72:75], v[164:167], v[228:231], v[72:75]
	v_mfma_f32_16x16x32_bf16 v[116:119], v[168:171], v[184:187], v[116:119]
	v_mfma_f32_16x16x32_bf16 v[112:115], v[176:179], v[184:187], v[112:115]
	v_mfma_f32_16x16x32_bf16 v[100:103], v[168:171], v[198:201], v[100:103]
	v_mfma_f32_16x16x32_bf16 v[96:99], v[176:179], v[198:201], v[96:99]
	v_mfma_f32_16x16x32_bf16 v[84:87], v[168:171], v[216:219], v[84:87]
	v_mfma_f32_16x16x32_bf16 v[80:83], v[176:179], v[216:219], v[80:83]
	v_mfma_f32_16x16x32_bf16 v[68:71], v[168:171], v[224:227], v[68:71]
	v_mfma_f32_16x16x32_bf16 v[64:67], v[176:179], v[224:227], v[64:67]
	v_mfma_f32_16x16x32_bf16 v[116:119], v[172:175], v[188:191], v[116:119]
	v_mfma_f32_16x16x32_bf16 v[112:115], v[180:183], v[188:191], v[112:115]
	v_mfma_f32_16x16x32_bf16 v[100:103], v[172:175], v[202:205], v[100:103]
	v_mfma_f32_16x16x32_bf16 v[96:99], v[180:183], v[202:205], v[96:99]
	v_mfma_f32_16x16x32_bf16 v[84:87], v[172:175], v[220:223], v[84:87]
	v_mfma_f32_16x16x32_bf16 v[80:83], v[180:183], v[220:223], v[80:83]
	v_mfma_f32_16x16x32_bf16 v[68:71], v[172:175], v[228:231], v[68:71]
	v_mfma_f32_16x16x32_bf16 v[64:67], v[180:183], v[228:231], v[64:67]
	s_barrier
; #define PG8_STAGE(bufoff, gbase, voff) do { _Pragma("unroll") for (int _i = 0; _i < 2; ++_i) \
;         __builtin_amdgcn_global_load_lds((const unsigned*)((const char*)(gbase) + (voff)[_i]), (LAS unsigned*)(lds + (bufoff) + ldsw + _i * 8192), 16, 0, 0); } while (0)
; #define PG8_LDA(dst, b, h) do { _Pragma("unroll") for (int m = 0; m < 4; ++m) _Pragma("unroll") for (int k = 0; k < 2; ++k) dst[m][k] = *(const LAS bf16x8*)(lds + PG8_SA(b, h) + aoff + m * 2048 + k * 1024); } while (0)
; #define PG8_MMA(ai, bj, At, Bt) do { __builtin_amdgcn_s_setprio(1); _Pragma("unroll") for (int m = 0; m < 4; ++m) _Pragma("unroll") for (int n = 0; n < 2; ++n) _Pragma("unroll") for (int k = 0; k < 2; ++k) \
;         acc[ai][bj][m][n] = __builtin_amdgcn_mfma_f32_16x16x32_bf16(Bt[n][k], At[m][k], acc[ai][bj][m][n], 0, 0, 0); __builtin_amdgcn_s_setprio(0); } while (0)
; #define PG8_WAIT_V(n) asm volatile("s_waitcnt vmcnt(" #n ")" ::: "memory")
; #define PG8_WAIT_L(n) asm volatile("s_waitcnt lgkmcnt(" #n ")" ::: "memory")
; #define PG8_BAR __builtin_amdgcn_s_barrier()
; #define PG8_SCHED __builtin_amdgcn_sched_barrier(0)
; template <class Epi, bool ALIGN_EPI, bool SP2 = PG8_SP2_DEFAULT>
; __device__ __forceinline__ void gemm_phase(LAS unsigned char* lds, const Gemm g, const StaticOrder& S, const Epi& E) {
;     ...
;             PG8_LDA(At, 1, 1); PG8_STAGE(PG8_SB(1, 0), b3, voffB); PG8_STAGE(PG8_SB(1, 1), b3 + hstepB, voffB); PG8_STAGE(PG8_SA(1, 0), a3, voffA);
;             PG8_WAIT_V(8); PG8_WAIT_L(0); PG8_BAR; PG8_MMA(1, 0, At, B0); PG8_MMA(1, 1, At, B1); PG8_BAR; PG8_SCHED;
;     ...
;         if constexpr (ALIGN_EPI) { if (wr == 0) PG8_BAR; }
	s_add_i32 s30, s51, s33
	v_lshl_add_u64 v[192:193], v[192:193], 0, s[14:15]
	s_mov_b32 m0, s30
	ds_read_b128 v[184:187], v153 offset:49152
	ds_read_b128 v[188:191], v153 offset:50176
	ds_read_b128 v[198:201], v153 offset:51200
	ds_read_b128 v[202:205], v153 offset:52224
	ds_read_b128 v[216:219], v153 offset:53248
	ds_read_b128 v[220:223], v153 offset:54272
	ds_read_b128 v[224:227], v153 offset:55296
	ds_read_b128 v[228:231], v153 offset:56320
	global_load_lds_dwordx4 v[192:193], off
	s_add_i32 m0, s30, 0x2000
	s_add_u32 s28, s28, 0x100080
	v_lshl_add_u64 v[192:193], v[206:207], 0, s[14:15]
	s_addc_u32 s29, s29, 0
	s_add_i32 s30, s52, s33
	global_load_lds_dwordx4 v[192:193], off
	v_lshl_add_u64 v[192:193], s[28:29], 0, v[130:131]
	s_mov_b32 m0, s30
	s_nop 0
	global_load_lds_dwordx4 v[192:193], off
	v_lshl_add_u64 v[192:193], s[28:29], 0, v[134:135]
	s_add_i32 m0, s30, 0x2000
	s_nop 0
	global_load_lds_dwordx4 v[192:193], off
	v_lshl_add_u64 v[192:193], v[210:211], 0, s[14:15]
	s_mov_b32 m0, s39
	s_nop 0
	global_load_lds_dwordx4 v[192:193], off
	v_lshl_add_u64 v[192:193], v[232:233], 0, s[14:15]
	s_mov_b32 m0, s40
	s_nop 0
	global_load_lds_dwordx4 v[192:193], off
	s_waitcnt vmcnt(8)
	s_waitcnt lgkmcnt(0)
	s_barrier
	v_mfma_f32_16x16x32_bf16 v[60:63], v[144:147], v[184:187], v[60:63]
	v_mfma_f32_16x16x32_bf16 v[56:59], v[160:163], v[184:187], v[56:59]
	v_mfma_f32_16x16x32_bf16 v[44:47], v[144:147], v[198:201], v[44:47]
	v_mfma_f32_16x16x32_bf16 v[40:43], v[160:163], v[198:201], v[40:43]
	v_mfma_f32_16x16x32_bf16 v[28:31], v[144:147], v[216:219], v[28:31]
	v_mfma_f32_16x16x32_bf16 v[24:27], v[160:163], v[216:219], v[24:27]
	v_mfma_f32_16x16x32_bf16 v[12:15], v[144:147], v[224:227], v[12:15]
	v_mfma_f32_16x16x32_bf16 v[8:11], v[160:163], v[224:227], v[8:11]
	v_mfma_f32_16x16x32_bf16 v[60:63], v[156:159], v[188:191], v[60:63]
	v_mfma_f32_16x16x32_bf16 v[56:59], v[164:167], v[188:191], v[56:59]
	v_mfma_f32_16x16x32_bf16 v[44:47], v[156:159], v[202:205], v[44:47]
	v_mfma_f32_16x16x32_bf16 v[40:43], v[164:167], v[202:205], v[40:43]
	v_mfma_f32_16x16x32_bf16 v[28:31], v[156:159], v[220:223], v[28:31]
	v_mfma_f32_16x16x32_bf16 v[24:27], v[164:167], v[220:223], v[24:27]
	v_mfma_f32_16x16x32_bf16 v[12:15], v[156:159], v[228:231], v[12:15]
	v_mfma_f32_16x16x32_bf16 v[8:11], v[164:167], v[228:231], v[8:11]
	v_mfma_f32_16x16x32_bf16 v[52:55], v[168:171], v[184:187], v[52:55]
	v_mfma_f32_16x16x32_bf16 v[48:51], v[176:179], v[184:187], v[48:51]
	v_mfma_f32_16x16x32_bf16 v[36:39], v[168:171], v[198:201], v[36:39]
	v_mfma_f32_16x16x32_bf16 v[32:35], v[176:179], v[198:201], v[32:35]
	v_mfma_f32_16x16x32_bf16 v[20:23], v[168:171], v[216:219], v[20:23]
	v_mfma_f32_16x16x32_bf16 v[16:19], v[176:179], v[216:219], v[16:19]
	v_mfma_f32_16x16x32_bf16 v[4:7], v[168:171], v[224:227], v[4:7]
	v_mfma_f32_16x16x32_bf16 v[0:3], v[176:179], v[224:227], v[0:3]
	v_mfma_f32_16x16x32_bf16 v[52:55], v[172:175], v[188:191], v[52:55]
	v_mfma_f32_16x16x32_bf16 v[48:51], v[180:183], v[188:191], v[48:51]
	v_mfma_f32_16x16x32_bf16 v[36:39], v[172:175], v[202:205], v[36:39]
	v_mfma_f32_16x16x32_bf16 v[32:35], v[180:183], v[202:205], v[32:35]
	v_mfma_f32_16x16x32_bf16 v[20:23], v[172:175], v[220:223], v[20:23]
	v_mfma_f32_16x16x32_bf16 v[16:19], v[180:183], v[220:223], v[16:19]
	v_mfma_f32_16x16x32_bf16 v[4:7], v[172:175], v[228:231], v[4:7]
	v_mfma_f32_16x16x32_bf16 v[0:3], v[180:183], v[228:231], v[0:3]
	s_barrier
	s_add_i32 s50, s50, 2
	s_add_u32 s26, s26, 0x100
	s_addc_u32 s27, s27, 0
	s_add_u32 s48, s48, 0x100
	s_addc_u32 s49, s49, 0
	s_cmp_gt_u32 s50, 61
	s_cbranch_scc0 .LBB0_506
	s_and_b64 vcc, exec, s[16:17]
	s_cbranch_vccz .LBB0_509
	s_barrier

; #define PG8_STAGE(bufoff, gbase, voff) do { _Pragma("unroll") for (int _i = 0; _i < 2; ++_i) \
;         __builtin_amdgcn_global_load_lds((const unsigned*)((const char*)(gbase) + (voff)[_i]), (LAS unsigned*)(lds + (bufoff) + ldsw + _i * 8192), 16, 0, 0); } while (0)
; #define PG8_LDA(dst, b, h) do { _Pragma("unroll") for (int m = 0; m < 4; ++m) _Pragma("unroll") for (int k = 0; k < 2; ++k) dst[m][k] = *(const LAS bf16x8*)(lds + PG8_SA(b, h) + aoff + m * 2048 + k * 1024); } while (0)
; #define PG8_LDB(dst, b, h) do { _Pragma("unroll") for (int n = 0; n < 2; ++n) _Pragma("unroll") for (int k = 0; k < 2; ++k) dst[n][k] = *(const LAS bf16x8*)(lds + PG8_SB(b, h) + boff + n * 2048 + k * 1024); } while (0)
; #define PG8_MMA(ai, bj, At, Bt) do { __builtin_amdgcn_s_setprio(1); _Pragma("unroll") for (int m = 0; m < 4; ++m) _Pragma("unroll") for (int n = 0; n < 2; ++n) _Pragma("unroll") for (int k = 0; k < 2; ++k) \
;         acc[ai][bj][m][n] = __builtin_amdgcn_mfma_f32_16x16x32_bf16(Bt[n][k], At[m][k], acc[ai][bj][m][n], 0, 0, 0); __builtin_amdgcn_s_setprio(0); } while (0)
; #define PG8_WAIT_V(n) asm volatile("s_waitcnt vmcnt(" #n ")" ::: "memory")
; #define PG8_WAIT_L(n) asm volatile("s_waitcnt lgkmcnt(" #n ")" ::: "memory")
; #define PG8_BAR __builtin_amdgcn_s_barrier()
; #define PG8_SCHED __builtin_amdgcn_sched_barrier(0)
; template <class Epi, bool ALIGN_EPI, bool SP2 = PG8_SP2_DEFAULT>
; __device__ __forceinline__ void gemm_phase(LAS unsigned char* lds, const Gemm g, const StaticOrder& S, const Epi& E) {
;     ...
;             PG8_LDB(B0, 0, 0); PG8_LDB(B1, 0, 1); PG8_SCHED; PG8_LDA(At, 0, 0); PG8_STAGE(PG8_SA(1, 1), a1 + hstepA, voffA);
;             PG8_WAIT_V(8); PG8_WAIT_L(0); PG8_BAR; PG8_MMA(0, 0, At, B0); PG8_MMA(0, 1, At, B1); PG8_BAR; PG8_SCHED;
;             PG8_LDA(At, 0, 1); PG8_STAGE(PG8_SB(0, 0), b2, voffB); PG8_STAGE(PG8_SB(0, 1), b2 + hstepB, voffB); PG8_STAGE(PG8_SA(0, 0), a2, voffA);
.LBB0_598:
	ds_read_b128 v[146:149], v155
	ds_read_b128 v[160:163], v155 offset:1024
	ds_read_b128 v[164:167], v155 offset:2048
	ds_read_b128 v[168:171], v155 offset:3072
	ds_read_b128 v[172:175], v156
	ds_read_b128 v[176:179], v156 offset:1024
	ds_read_b128 v[180:183], v156 offset:2048
	ds_read_b128 v[184:187], v156 offset:3072
	s_add_u32 s24, s22, 0xfff00080
	s_addc_u32 s25, s23, -1
	s_cmp_eq_u32 s47, 60
	s_cselect_b32 s27, s3, s25
	s_cselect_b32 s26, s7, s24
	s_cselect_b32 s25, s9, s45
	s_cselect_b32 s24, s17, s44
	v_lshl_add_u64 v[192:193], s[22:23], 0, v[138:139]
	s_add_i32 m0, s30, 0xc000
	ds_read_b128 v[188:191], v157
	ds_read_b128 v[198:201], v157 offset:1024
	ds_read_b128 v[202:205], v157 offset:2048
	ds_read_b128 v[214:217], v157 offset:3072
	ds_read_b128 v[218:221], v157 offset:4096
	ds_read_b128 v[222:225], v157 offset:5120
	ds_read_b128 v[226:229], v157 offset:6144
	ds_read_b128 v[230:233], v157 offset:7168
	global_load_lds_dwordx4 v[192:193], off
	v_lshl_add_u64 v[192:193], s[22:23], 0, v[140:141]
	s_add_i32 m0, s30, 0xe000
	s_nop 0
	global_load_lds_dwordx4 v[192:193], off
	s_waitcnt vmcnt(8)
	s_waitcnt lgkmcnt(0)
	s_barrier
	v_mfma_f32_16x16x32_bf16 v[124:127], v[146:149], v[188:191], v[124:127]
	v_mfma_f32_16x16x32_bf16 v[120:123], v[164:167], v[188:191], v[120:123]
	v_mfma_f32_16x16x32_bf16 v[108:111], v[146:149], v[202:205], v[108:111]
	v_mfma_f32_16x16x32_bf16 v[104:107], v[164:167], v[202:205], v[104:107]
	v_mfma_f32_16x16x32_bf16 v[92:95], v[146:149], v[218:221], v[92:95]
	v_mfma_f32_16x16x32_bf16 v[88:91], v[164:167], v[218:221], v[88:91]
	v_mfma_f32_16x16x32_bf16 v[76:79], v[146:149], v[226:229], v[76:79]
	v_mfma_f32_16x16x32_bf16 v[72:75], v[164:167], v[226:229], v[72:75]
	v_mfma_f32_16x16x32_bf16 v[124:127], v[160:163], v[198:201], v[124:127]
	v_mfma_f32_16x16x32_bf16 v[120:123], v[168:171], v[198:201], v[120:123]
	v_mfma_f32_16x16x32_bf16 v[108:111], v[160:163], v[214:217], v[108:111]
	v_mfma_f32_16x16x32_bf16 v[104:107], v[168:171], v[214:217], v[104:107]
	v_mfma_f32_16x16x32_bf16 v[92:95], v[160:163], v[222:225], v[92:95]
	v_mfma_f32_16x16x32_bf16 v[88:91], v[168:171], v[222:225], v[88:91]
	v_mfma_f32_16x16x32_bf16 v[76:79], v[160:163], v[230:233], v[76:79]
	v_mfma_f32_16x16x32_bf16 v[72:75], v[168:171], v[230:233], v[72:75]
	v_mfma_f32_16x16x32_bf16 v[116:119], v[172:175], v[188:191], v[116:119]
	v_mfma_f32_16x16x32_bf16 v[112:115], v[180:183], v[188:191], v[112:115]
	v_mfma_f32_16x16x32_bf16 v[100:103], v[172:175], v[202:205], v[100:103]
	v_mfma_f32_16x16x32_bf16 v[96:99], v[180:183], v[202:205], v[96:99]
	v_mfma_f32_16x16x32_bf16 v[84:87], v[172:175], v[218:221], v[84:87]
	v_mfma_f32_16x16x32_bf16 v[80:83], v[180:183], v[218:221], v[80:83]
	v_mfma_f32_16x16x32_bf16 v[68:71], v[172:175], v[226:229], v[68:71]
	v_mfma_f32_16x16x32_bf16 v[64:67], v[180:183], v[226:229], v[64:67]
	v_mfma_f32_16x16x32_bf16 v[116:119], v[176:179], v[198:201], v[116:119]
	v_mfma_f32_16x16x32_bf16 v[112:115], v[184:187], v[198:201], v[112:115]
	v_mfma_f32_16x16x32_bf16 v[100:103], v[176:179], v[214:217], v[100:103]
	v_mfma_f32_16x16x32_bf16 v[96:99], v[184:187], v[214:217], v[96:99]
	v_mfma_f32_16x16x32_bf16 v[84:87], v[176:179], v[222:225], v[84:87]
	v_mfma_f32_16x16x32_bf16 v[80:83], v[184:187], v[222:225], v[80:83]
	v_mfma_f32_16x16x32_bf16 v[68:71], v[176:179], v[230:233], v[68:71]
	v_mfma_f32_16x16x32_bf16 v[64:67], v[184:187], v[230:233], v[64:67]
	s_barrier
	s_add_i32 s48, s41, s29
	v_lshl_add_u64 v[192:193], s[24:25], 0, v[130:131]
	s_mov_b32 m0, s48
	ds_read_b128 v[188:191], v157 offset:16384
	ds_read_b128 v[198:201], v157 offset:17408
	ds_read_b128 v[202:205], v157 offset:18432
	ds_read_b128 v[214:217], v157 offset:19456
	ds_read_b128 v[218:221], v157 offset:20480
	ds_read_b128 v[222:225], v157 offset:21504
	ds_read_b128 v[226:229], v157 offset:22528
	ds_read_b128 v[230:233], v157 offset:23552
	global_load_lds_dwordx4 v[192:193], off
	s_add_i32 m0, s48, 0x2000
	s_add_u32 s48, s24, 0x100000
	v_lshl_add_u64 v[206:207], s[24:25], 0, v[134:135]
	s_addc_u32 s49, s25, 0
	s_add_i32 s50, s42, s29
	global_load_lds_dwordx4 v[206:207], off
	v_lshl_add_u64 v[210:211], s[48:49], 0, v[130:131]
	s_mov_b32 m0, s50
	v_lshl_add_u64 v[234:235], s[26:27], 0, v[132:133]
	global_load_lds_dwordx4 v[210:211], off
	v_lshl_add_u64 v[210:211], s[48:49], 0, v[134:135]
	s_add_i32 m0, s50, 0x2000
	s_nop 0
	global_load_lds_dwordx4 v[210:211], off
	v_lshl_add_u64 v[210:211], s[26:27], 0, v[128:129]
	s_mov_b32 m0, s30
	s_nop 0
	global_load_lds_dwordx4 v[210:211], off
	s_mov_b32 m0, s31
	s_nop 0
	global_load_lds_dwordx4 v[234:235], off
	s_waitcnt vmcnt(8)
	s_waitcnt lgkmcnt(0)
	s_barrier
; #define PG8_STAGE(bufoff, gbase, voff) do { _Pragma("unroll") for (int _i = 0; _i < 2; ++_i) \
;         __builtin_amdgcn_global_load_lds((const unsigned*)((const char*)(gbase) + (voff)[_i]), (LAS unsigned*)(lds + (bufoff) + ldsw + _i * 8192), 16, 0, 0); } while (0)
; #define PG8_LDA(dst, b, h) do { _Pragma("unroll") for (int m = 0; m < 4; ++m) _Pragma("unroll") for (int k = 0; k < 2; ++k) dst[m][k] = *(const LAS bf16x8*)(lds + PG8_SA(b, h) + aoff + m * 2048 + k * 1024); } while (0)
; #define PG8_LDB(dst, b, h) do { _Pragma("unroll") for (int n = 0; n < 2; ++n) _Pragma("unroll") for (int k = 0; k < 2; ++k) dst[n][k] = *(const LAS bf16x8*)(lds + PG8_SB(b, h) + boff + n * 2048 + k * 1024); } while (0)
; #define PG8_MMA(ai, bj, At, Bt) do { __builtin_amdgcn_s_setprio(1); _Pragma("unroll") for (int m = 0; m < 4; ++m) _Pragma("unroll") for (int n = 0; n < 2; ++n) _Pragma("unroll") for (int k = 0; k < 2; ++k) \
;         acc[ai][bj][m][n] = __builtin_amdgcn_mfma_f32_16x16x32_bf16(Bt[n][k], At[m][k], acc[ai][bj][m][n], 0, 0, 0); __builtin_amdgcn_s_setprio(0); } while (0)
; #define PG8_WAIT_V(n) asm volatile("s_waitcnt vmcnt(" #n ")" ::: "memory")
; #define PG8_WAIT_L(n) asm volatile("s_waitcnt lgkmcnt(" #n ")" ::: "memory")
; #define PG8_BAR __builtin_amdgcn_s_barrier()
; #define PG8_SCHED __builtin_amdgcn_sched_barrier(0)
; template <class Epi, bool ALIGN_EPI, bool SP2 = PG8_SP2_DEFAULT>
; __device__ __forceinline__ void gemm_phase(LAS unsigned char* lds, const Gemm g, const StaticOrder& S, const Epi& E) {
;     ...
;             PG8_WAIT_V(8); PG8_WAIT_L(0); PG8_BAR; PG8_MMA(1, 0, At, B0); PG8_MMA(1, 1, At, B1); PG8_BAR; PG8_SCHED;
;             PG8_LDB(B0, 1, 0); PG8_LDB(B1, 1, 1); PG8_SCHED; PG8_LDA(At, 1, 0); PG8_STAGE(PG8_SA(0, 1), a2 + hstepA, voffA);
;             PG8_WAIT_V(8); PG8_WAIT_L(0); PG8_BAR; PG8_MMA(0, 0, At, B0); PG8_MMA(0, 1, At, B1); PG8_BAR; PG8_SCHED;
	v_mfma_f32_16x16x32_bf16 v[60:63], v[146:149], v[188:191], v[60:63]
	v_mfma_f32_16x16x32_bf16 v[56:59], v[164:167], v[188:191], v[56:59]
	v_mfma_f32_16x16x32_bf16 v[44:47], v[146:149], v[202:205], v[44:47]
	v_mfma_f32_16x16x32_bf16 v[40:43], v[164:167], v[202:205], v[40:43]
	v_mfma_f32_16x16x32_bf16 v[28:31], v[146:149], v[218:221], v[28:31]
	v_mfma_f32_16x16x32_bf16 v[24:27], v[164:167], v[218:221], v[24:27]
	v_mfma_f32_16x16x32_bf16 v[12:15], v[146:149], v[226:229], v[12:15]
	v_mfma_f32_16x16x32_bf16 v[8:11], v[164:167], v[226:229], v[8:11]
	v_mfma_f32_16x16x32_bf16 v[60:63], v[160:163], v[198:201], v[60:63]
	v_mfma_f32_16x16x32_bf16 v[56:59], v[168:171], v[198:201], v[56:59]
	v_mfma_f32_16x16x32_bf16 v[44:47], v[160:163], v[214:217], v[44:47]
	v_mfma_f32_16x16x32_bf16 v[40:43], v[168:171], v[214:217], v[40:43]
	v_mfma_f32_16x16x32_bf16 v[28:31], v[160:163], v[222:225], v[28:31]
	v_mfma_f32_16x16x32_bf16 v[24:27], v[168:171], v[222:225], v[24:27]
	v_mfma_f32_16x16x32_bf16 v[12:15], v[160:163], v[230:233], v[12:15]
	v_mfma_f32_16x16x32_bf16 v[8:11], v[168:171], v[230:233], v[8:11]
	v_mfma_f32_16x16x32_bf16 v[52:55], v[172:175], v[188:191], v[52:55]
	v_mfma_f32_16x16x32_bf16 v[48:51], v[180:183], v[188:191], v[48:51]
	v_mfma_f32_16x16x32_bf16 v[36:39], v[172:175], v[202:205], v[36:39]
	v_mfma_f32_16x16x32_bf16 v[32:35], v[180:183], v[202:205], v[32:35]
	v_mfma_f32_16x16x32_bf16 v[20:23], v[172:175], v[218:221], v[20:23]
	v_mfma_f32_16x16x32_bf16 v[16:19], v[180:183], v[218:221], v[16:19]
	v_mfma_f32_16x16x32_bf16 v[4:7], v[172:175], v[226:229], v[4:7]
	v_mfma_f32_16x16x32_bf16 v[0:3], v[180:183], v[226:229], v[0:3]
	v_mfma_f32_16x16x32_bf16 v[52:55], v[176:179], v[198:201], v[52:55]
	v_mfma_f32_16x16x32_bf16 v[48:51], v[184:187], v[198:201], v[48:51]
	v_mfma_f32_16x16x32_bf16 v[36:39], v[176:179], v[214:217], v[36:39]
	v_mfma_f32_16x16x32_bf16 v[32:35], v[184:187], v[214:217], v[32:35]
	v_mfma_f32_16x16x32_bf16 v[20:23], v[176:179], v[222:225], v[20:23]
	v_mfma_f32_16x16x32_bf16 v[16:19], v[184:187], v[222:225], v[16:19]
	v_mfma_f32_16x16x32_bf16 v[4:7], v[176:179], v[230:233], v[4:7]
	v_mfma_f32_16x16x32_bf16 v[0:3], v[184:187], v[230:233], v[0:3]
	s_barrier
	s_add_i32 s48, 0, 0x18000
	v_add_u32_e32 v150, s48, v152
	s_add_i32 s49, 0, 0x1c000
	ds_read_b128 v[146:149], v150
	ds_read_b128 v[160:163], v150 offset:1024
	ds_read_b128 v[164:167], v150 offset:2048
	ds_read_b128 v[168:171], v150 offset:3072
	v_add_u32_e32 v150, s49, v152
	ds_read_b128 v[172:175], v150
	ds_read_b128 v[176:179], v150 offset:1024
	ds_read_b128 v[180:183], v150 offset:2048
	ds_read_b128 v[184:187], v150 offset:3072
	s_add_u32 s26, s26, 0x100000
	s_addc_u32 s27, s27, 0
	s_mov_b32 m0, s33
	v_lshl_add_u64 v[236:237], s[26:27], 0, v[128:129]
	ds_read_b128 v[188:191], v157 offset:32768
	ds_read_b128 v[198:201], v157 offset:33792
	ds_read_b128 v[202:205], v157 offset:34816
	ds_read_b128 v[214:217], v157 offset:35840
	ds_read_b128 v[218:221], v157 offset:36864
	ds_read_b128 v[222:225], v157 offset:37888
	ds_read_b128 v[226:229], v157 offset:38912
	ds_read_b128 v[230:233], v157 offset:39936
	global_load_lds_dwordx4 v[236:237], off
	v_lshl_add_u64 v[236:237], s[26:27], 0, v[132:133]
	s_mov_b32 m0, s34
	s_nop 0
	global_load_lds_dwordx4 v[236:237], off
	s_waitcnt vmcnt(8)
	s_waitcnt lgkmcnt(0)
	s_barrier
	v_mfma_f32_16x16x32_bf16 v[124:127], v[146:149], v[188:191], v[124:127]
	v_mfma_f32_16x16x32_bf16 v[120:123], v[164:167], v[188:191], v[120:123]
	v_mfma_f32_16x16x32_bf16 v[108:111], v[146:149], v[202:205], v[108:111]
	v_mfma_f32_16x16x32_bf16 v[104:107], v[164:167], v[202:205], v[104:107]
	v_mfma_f32_16x16x32_bf16 v[92:95], v[146:149], v[218:221], v[92:95]
	v_mfma_f32_16x16x32_bf16 v[88:91], v[164:167], v[218:221], v[88:91]
	v_mfma_f32_16x16x32_bf16 v[76:79], v[146:149], v[226:229], v[76:79]
	v_mfma_f32_16x16x32_bf16 v[72:75], v[164:167], v[226:229], v[72:75]
	v_mfma_f32_16x16x32_bf16 v[124:127], v[160:163], v[198:201], v[124:127]
	v_mfma_f32_16x16x32_bf16 v[120:123], v[168:171], v[198:201], v[120:123]
	v_mfma_f32_16x16x32_bf16 v[108:111], v[160:163], v[214:217], v[108:111]
	v_mfma_f32_16x16x32_bf16 v[104:107], v[168:171], v[214:217], v[104:107]
	v_mfma_f32_16x16x32_bf16 v[92:95], v[160:163], v[222:225], v[92:95]
	v_mfma_f32_16x16x32_bf16 v[88:91], v[168:171], v[222:225], v[88:91]
	v_mfma_f32_16x16x32_bf16 v[76:79], v[160:163], v[230:233], v[76:79]
	v_mfma_f32_16x16x32_bf16 v[72:75], v[168:171], v[230:233], v[72:75]
	v_mfma_f32_16x16x32_bf16 v[116:119], v[172:175], v[188:191], v[116:119]
	v_mfma_f32_16x16x32_bf16 v[112:115], v[180:183], v[188:191], v[112:115]
	v_mfma_f32_16x16x32_bf16 v[100:103], v[172:175], v[202:205], v[100:103]
	v_mfma_f32_16x16x32_bf16 v[96:99], v[180:183], v[202:205], v[96:99]
	v_mfma_f32_16x16x32_bf16 v[84:87], v[172:175], v[218:221], v[84:87]
	v_mfma_f32_16x16x32_bf16 v[80:83], v[180:183], v[218:221], v[80:83]
	v_mfma_f32_16x16x32_bf16 v[68:71], v[172:175], v[226:229], v[68:71]
	v_mfma_f32_16x16x32_bf16 v[64:67], v[180:183], v[226:229], v[64:67]
	v_mfma_f32_16x16x32_bf16 v[116:119], v[176:179], v[198:201], v[116:119]
	v_mfma_f32_16x16x32_bf16 v[112:115], v[184:187], v[198:201], v[112:115]
	v_mfma_f32_16x16x32_bf16 v[100:103], v[176:179], v[214:217], v[100:103]
	v_mfma_f32_16x16x32_bf16 v[96:99], v[184:187], v[214:217], v[96:99]
	v_mfma_f32_16x16x32_bf16 v[84:87], v[176:179], v[222:225], v[84:87]
	v_mfma_f32_16x16x32_bf16 v[80:83], v[184:187], v[222:225], v[80:83]
	v_mfma_f32_16x16x32_bf16 v[68:71], v[176:179], v[230:233], v[68:71]
	v_mfma_f32_16x16x32_bf16 v[64:67], v[184:187], v[230:233], v[64:67]
	s_barrier
; #define PG8_STAGE(bufoff, gbase, voff) do { _Pragma("unroll") for (int _i = 0; _i < 2; ++_i) \
;         __builtin_amdgcn_global_load_lds((const unsigned*)((const char*)(gbase) + (voff)[_i]), (LAS unsigned*)(lds + (bufoff) + ldsw + _i * 8192), 16, 0, 0); } while (0)
; #define PG8_LDA(dst, b, h) do { _Pragma("unroll") for (int m = 0; m < 4; ++m) _Pragma("unroll") for (int k = 0; k < 2; ++k) dst[m][k] = *(const LAS bf16x8*)(lds + PG8_SA(b, h) + aoff + m * 2048 + k * 1024); } while (0)
; #define PG8_MMA(ai, bj, At, Bt) do { __builtin_amdgcn_s_setprio(1); _Pragma("unroll") for (int m = 0; m < 4; ++m) _Pragma("unroll") for (int n = 0; n < 2; ++n) _Pragma("unroll") for (int k = 0; k < 2; ++k) \
;         acc[ai][bj][m][n] = __builtin_amdgcn_mfma_f32_16x16x32_bf16(Bt[n][k], At[m][k], acc[ai][bj][m][n], 0, 0, 0); __builtin_amdgcn_s_setprio(0); } while (0)
; #define PG8_WAIT_V(n) asm volatile("s_waitcnt vmcnt(" #n ")" ::: "memory")
; #define PG8_WAIT_L(n) asm volatile("s_waitcnt lgkmcnt(" #n ")" ::: "memory")
; #define PG8_BAR __builtin_amdgcn_s_barrier()
; #define PG8_SCHED __builtin_amdgcn_sched_barrier(0)
; template <class Epi, bool ALIGN_EPI, bool SP2 = PG8_SP2_DEFAULT>
; __device__ __forceinline__ void gemm_phase(LAS unsigned char* lds, const Gemm g, const StaticOrder& S, const Epi& E) {
;     ...
;             PG8_LDA(At, 1, 1); PG8_STAGE(PG8_SB(1, 0), b3, voffB); PG8_STAGE(PG8_SB(1, 1), b3 + hstepB, voffB); PG8_STAGE(PG8_SA(1, 0), a3, voffA);
;             PG8_WAIT_V(8); PG8_WAIT_L(0); PG8_BAR; PG8_MMA(1, 0, At, B0); PG8_MMA(1, 1, At, B1); PG8_BAR; PG8_SCHED;
;     ...
;         if constexpr (ALIGN_EPI) { if (wr == 0) PG8_BAR; }
	s_add_i32 s26, s48, s29
	v_lshl_add_u64 v[192:193], v[192:193], 0, s[12:13]
	s_mov_b32 m0, s26
	ds_read_b128 v[188:191], v157 offset:49152
	ds_read_b128 v[198:201], v157 offset:50176
	ds_read_b128 v[202:205], v157 offset:51200
	ds_read_b128 v[214:217], v157 offset:52224
	ds_read_b128 v[218:221], v157 offset:53248
	ds_read_b128 v[222:225], v157 offset:54272
	ds_read_b128 v[226:229], v157 offset:55296
	ds_read_b128 v[230:233], v157 offset:56320
	global_load_lds_dwordx4 v[192:193], off
	s_add_i32 m0, s26, 0x2000
	s_add_u32 s24, s24, 0x100080
	v_lshl_add_u64 v[192:193], v[206:207], 0, s[12:13]
	s_addc_u32 s25, s25, 0
	s_add_i32 s26, s49, s29
	global_load_lds_dwordx4 v[192:193], off
	v_lshl_add_u64 v[192:193], s[24:25], 0, v[130:131]
	s_mov_b32 m0, s26
	s_nop 0
	global_load_lds_dwordx4 v[192:193], off
	v_lshl_add_u64 v[192:193], s[24:25], 0, v[134:135]
	s_add_i32 m0, s26, 0x2000
	s_nop 0
	global_load_lds_dwordx4 v[192:193], off
	v_lshl_add_u64 v[192:193], v[210:211], 0, s[12:13]
	s_mov_b32 m0, s36
	s_nop 0
	global_load_lds_dwordx4 v[192:193], off
	v_lshl_add_u64 v[192:193], v[234:235], 0, s[12:13]
	s_mov_b32 m0, s37
	s_nop 0
	global_load_lds_dwordx4 v[192:193], off
	s_waitcnt vmcnt(8)
	s_waitcnt lgkmcnt(0)
	s_barrier
	v_mfma_f32_16x16x32_bf16 v[60:63], v[146:149], v[188:191], v[60:63]
	v_mfma_f32_16x16x32_bf16 v[56:59], v[164:167], v[188:191], v[56:59]
	v_mfma_f32_16x16x32_bf16 v[44:47], v[146:149], v[202:205], v[44:47]
	v_mfma_f32_16x16x32_bf16 v[40:43], v[164:167], v[202:205], v[40:43]
	v_mfma_f32_16x16x32_bf16 v[28:31], v[146:149], v[218:221], v[28:31]
	v_mfma_f32_16x16x32_bf16 v[24:27], v[164:167], v[218:221], v[24:27]
	v_mfma_f32_16x16x32_bf16 v[12:15], v[146:149], v[226:229], v[12:15]
	v_mfma_f32_16x16x32_bf16 v[8:11], v[164:167], v[226:229], v[8:11]
	v_mfma_f32_16x16x32_bf16 v[60:63], v[160:163], v[198:201], v[60:63]
	v_mfma_f32_16x16x32_bf16 v[56:59], v[168:171], v[198:201], v[56:59]
	v_mfma_f32_16x16x32_bf16 v[44:47], v[160:163], v[214:217], v[44:47]
	v_mfma_f32_16x16x32_bf16 v[40:43], v[168:171], v[214:217], v[40:43]
	v_mfma_f32_16x16x32_bf16 v[28:31], v[160:163], v[222:225], v[28:31]
	v_mfma_f32_16x16x32_bf16 v[24:27], v[168:171], v[222:225], v[24:27]
	v_mfma_f32_16x16x32_bf16 v[12:15], v[160:163], v[230:233], v[12:15]
	v_mfma_f32_16x16x32_bf16 v[8:11], v[168:171], v[230:233], v[8:11]
	v_mfma_f32_16x16x32_bf16 v[52:55], v[172:175], v[188:191], v[52:55]
	v_mfma_f32_16x16x32_bf16 v[48:51], v[180:183], v[188:191], v[48:51]
	v_mfma_f32_16x16x32_bf16 v[36:39], v[172:175], v[202:205], v[36:39]
	v_mfma_f32_16x16x32_bf16 v[32:35], v[180:183], v[202:205], v[32:35]
	v_mfma_f32_16x16x32_bf16 v[20:23], v[172:175], v[218:221], v[20:23]
	v_mfma_f32_16x16x32_bf16 v[16:19], v[180:183], v[218:221], v[16:19]
	v_mfma_f32_16x16x32_bf16 v[4:7], v[172:175], v[226:229], v[4:7]
	v_mfma_f32_16x16x32_bf16 v[0:3], v[180:183], v[226:229], v[0:3]
	v_mfma_f32_16x16x32_bf16 v[52:55], v[176:179], v[198:201], v[52:55]
	v_mfma_f32_16x16x32_bf16 v[48:51], v[184:187], v[198:201], v[48:51]
	v_mfma_f32_16x16x32_bf16 v[36:39], v[176:179], v[214:217], v[36:39]
	v_mfma_f32_16x16x32_bf16 v[32:35], v[184:187], v[214:217], v[32:35]
	v_mfma_f32_16x16x32_bf16 v[20:23], v[176:179], v[222:225], v[20:23]
	v_mfma_f32_16x16x32_bf16 v[16:19], v[184:187], v[222:225], v[16:19]
	v_mfma_f32_16x16x32_bf16 v[4:7], v[176:179], v[230:233], v[4:7]
	v_mfma_f32_16x16x32_bf16 v[0:3], v[184:187], v[230:233], v[0:3]
	s_barrier
	s_add_i32 s47, s47, 2
	s_add_u32 s22, s22, 0x100
	s_addc_u32 s23, s23, 0
	s_add_u32 s44, s44, 0x100
	s_addc_u32 s45, s45, 0
	s_cmp_gt_u32 s47, 61
	s_cbranch_scc0 .LBB0_598
	s_and_b64 vcc, exec, s[14:15]
	s_cbranch_vccz .LBB0_601
	s_barrier

; #define PG8_STAGE(bufoff, gbase, voff) do { _Pragma("unroll") for (int _i = 0; _i < 2; ++_i) \
;         __builtin_amdgcn_global_load_lds((const unsigned*)((const char*)(gbase) + (voff)[_i]), (LAS unsigned*)(lds + (bufoff) + ldsw + _i * 8192), 16, 0, 0); } while (0)
; #define PG8_LDA(dst, b, h) do { _Pragma("unroll") for (int m = 0; m < 4; ++m) _Pragma("unroll") for (int k = 0; k < 2; ++k) dst[m][k] = *(const LAS bf16x8*)(lds + PG8_SA(b, h) + aoff + m * 2048 + k * 1024); } while (0)
; #define PG8_LDB(dst, b, h) do { _Pragma("unroll") for (int n = 0; n < 2; ++n) _Pragma("unroll") for (int k = 0; k < 2; ++k) dst[n][k] = *(const LAS bf16x8*)(lds + PG8_SB(b, h) + boff + n * 2048 + k * 1024); } while (0)
; #define PG8_MMA(ai, bj, At, Bt) do { __builtin_amdgcn_s_setprio(1); _Pragma("unroll") for (int m = 0; m < 4; ++m) _Pragma("unroll") for (int n = 0; n < 2; ++n) _Pragma("unroll") for (int k = 0; k < 2; ++k) \
;         acc[ai][bj][m][n] = __builtin_amdgcn_mfma_f32_16x16x32_bf16(Bt[n][k], At[m][k], acc[ai][bj][m][n], 0, 0, 0); __builtin_amdgcn_s_setprio(0); } while (0)
; #define PG8_WAIT_V(n) asm volatile("s_waitcnt vmcnt(" #n ")" ::: "memory")
; #define PG8_WAIT_L(n) asm volatile("s_waitcnt lgkmcnt(" #n ")" ::: "memory")
; #define PG8_BAR __builtin_amdgcn_s_barrier()
; #define PG8_SCHED __builtin_amdgcn_sched_barrier(0)
; template <class Epi, bool ALIGN_EPI, bool SP2 = PG8_SP2_DEFAULT>
; __device__ __forceinline__ void gemm_phase(LAS unsigned char* lds, const Gemm g, const StaticOrder& S, const Epi& E) {
;     ...
;             PG8_LDB(B0, 0, 0); PG8_LDB(B1, 0, 1); PG8_SCHED; PG8_LDA(At, 0, 0); PG8_STAGE(PG8_SA(1, 1), a1 + hstepA, voffA);
;             PG8_WAIT_V(8); PG8_WAIT_L(0); PG8_BAR; PG8_MMA(0, 0, At, B0); PG8_MMA(0, 1, At, B1); PG8_BAR; PG8_SCHED;
;             PG8_LDA(At, 0, 1); PG8_STAGE(PG8_SB(0, 0), b2, voffB); PG8_STAGE(PG8_SB(0, 1), b2 + hstepB, voffB); PG8_STAGE(PG8_SA(0, 0), a2, voffA);
.LBB0_804:
	ds_read_b128 v[144:147], v153
	ds_read_b128 v[156:159], v153 offset:1024
	ds_read_b128 v[160:163], v153 offset:2048
	ds_read_b128 v[164:167], v153 offset:3072
	ds_read_b128 v[168:171], v154
	ds_read_b128 v[172:175], v154 offset:1024
	ds_read_b128 v[176:179], v154 offset:2048
	ds_read_b128 v[180:183], v154 offset:3072
	s_add_u32 s22, s20, 0x100
	s_addc_u32 s23, s21, 0
	s_cmpk_eq_i32 s49, 0xa8
	s_cselect_b32 s27, s5, s23
	s_cselect_b32 s26, s4, s22
	s_cselect_b32 s25, s19, s48
	s_cselect_b32 s24, s18, s47
	v_lshl_add_u64 v[148:149], s[20:21], 0, v[136:137]
	s_add_i32 m0, s31, 0xc000
	ds_read_b128 v[184:187], v155
	ds_read_b128 v[188:191], v155 offset:1024
	ds_read_b128 v[192:195], v155 offset:2048
	ds_read_b128 v[196:199], v155 offset:3072
	ds_read_b128 v[200:203], v155 offset:4096
	ds_read_b128 v[204:207], v155 offset:5120
	ds_read_b128 v[208:211], v155 offset:6144
	ds_read_b128 v[212:215], v155 offset:7168
	global_load_lds_dwordx4 v[148:149], off
	v_lshl_add_u64 v[148:149], s[20:21], 0, v[138:139]
	s_add_i32 m0, s31, 0xe000
	s_nop 0
	global_load_lds_dwordx4 v[148:149], off
	s_waitcnt vmcnt(8)
	s_waitcnt lgkmcnt(0)
	s_barrier
	v_mfma_f32_16x16x32_bf16 v[124:127], v[144:147], v[184:187], v[124:127]
	v_mfma_f32_16x16x32_bf16 v[120:123], v[160:163], v[184:187], v[120:123]
	v_mfma_f32_16x16x32_bf16 v[108:111], v[144:147], v[192:195], v[108:111]
	v_mfma_f32_16x16x32_bf16 v[104:107], v[160:163], v[192:195], v[104:107]
	v_mfma_f32_16x16x32_bf16 v[92:95], v[144:147], v[200:203], v[92:95]
	v_mfma_f32_16x16x32_bf16 v[88:91], v[160:163], v[200:203], v[88:91]
	v_mfma_f32_16x16x32_bf16 v[76:79], v[144:147], v[208:211], v[76:79]
	v_mfma_f32_16x16x32_bf16 v[72:75], v[160:163], v[208:211], v[72:75]
	v_mfma_f32_16x16x32_bf16 v[124:127], v[156:159], v[188:191], v[124:127]
	v_mfma_f32_16x16x32_bf16 v[120:123], v[164:167], v[188:191], v[120:123]
	v_mfma_f32_16x16x32_bf16 v[108:111], v[156:159], v[196:199], v[108:111]
	v_mfma_f32_16x16x32_bf16 v[104:107], v[164:167], v[196:199], v[104:107]
	v_mfma_f32_16x16x32_bf16 v[92:95], v[156:159], v[204:207], v[92:95]
	v_mfma_f32_16x16x32_bf16 v[88:91], v[164:167], v[204:207], v[88:91]
	v_mfma_f32_16x16x32_bf16 v[76:79], v[156:159], v[212:215], v[76:79]
	v_mfma_f32_16x16x32_bf16 v[72:75], v[164:167], v[212:215], v[72:75]
	v_mfma_f32_16x16x32_bf16 v[116:119], v[168:171], v[184:187], v[116:119]
	v_mfma_f32_16x16x32_bf16 v[112:115], v[176:179], v[184:187], v[112:115]
	v_mfma_f32_16x16x32_bf16 v[100:103], v[168:171], v[192:195], v[100:103]
	v_mfma_f32_16x16x32_bf16 v[96:99], v[176:179], v[192:195], v[96:99]
	v_mfma_f32_16x16x32_bf16 v[84:87], v[168:171], v[200:203], v[84:87]
	v_mfma_f32_16x16x32_bf16 v[80:83], v[176:179], v[200:203], v[80:83]
	v_mfma_f32_16x16x32_bf16 v[68:71], v[168:171], v[208:211], v[68:71]
	v_mfma_f32_16x16x32_bf16 v[64:67], v[176:179], v[208:211], v[64:67]
	v_mfma_f32_16x16x32_bf16 v[116:119], v[172:175], v[188:191], v[116:119]
	v_mfma_f32_16x16x32_bf16 v[112:115], v[180:183], v[188:191], v[112:115]
	v_mfma_f32_16x16x32_bf16 v[100:103], v[172:175], v[196:199], v[100:103]
	v_mfma_f32_16x16x32_bf16 v[96:99], v[180:183], v[196:199], v[96:99]
	v_mfma_f32_16x16x32_bf16 v[84:87], v[172:175], v[204:207], v[84:87]
	v_mfma_f32_16x16x32_bf16 v[80:83], v[180:183], v[204:207], v[80:83]
	v_mfma_f32_16x16x32_bf16 v[68:71], v[172:175], v[212:215], v[68:71]
	v_mfma_f32_16x16x32_bf16 v[64:67], v[180:183], v[212:215], v[64:67]
	s_barrier
	s_add_i32 s20, s40, s28
	v_lshl_add_u64 v[148:149], s[24:25], 0, v[130:131]
	s_mov_b32 m0, s20
	ds_read_b128 v[184:187], v155 offset:16384
	ds_read_b128 v[188:191], v155 offset:17408
	ds_read_b128 v[192:195], v155 offset:18432
	ds_read_b128 v[196:199], v155 offset:19456
	ds_read_b128 v[200:203], v155 offset:20480
	ds_read_b128 v[204:207], v155 offset:21504
	ds_read_b128 v[208:211], v155 offset:22528
	ds_read_b128 v[212:215], v155 offset:23552
	global_load_lds_dwordx4 v[148:149], off
	s_add_i32 m0, s20, 0x2000
	s_add_u32 s20, s24, 0x2b0000
	v_lshl_add_u64 v[216:217], s[24:25], 0, v[134:135]
	s_addc_u32 s21, s25, 0
	s_add_i32 s50, s41, s28
	global_load_lds_dwordx4 v[216:217], off
	v_lshl_add_u64 v[218:219], s[20:21], 0, v[130:131]
	s_mov_b32 m0, s50
	v_lshl_add_u64 v[220:221], s[26:27], 0, v[132:133]
	global_load_lds_dwordx4 v[218:219], off
	v_lshl_add_u64 v[218:219], s[20:21], 0, v[134:135]
	s_add_i32 m0, s50, 0x2000
	s_nop 0
	global_load_lds_dwordx4 v[218:219], off
	v_lshl_add_u64 v[218:219], s[26:27], 0, v[128:129]
	s_mov_b32 m0, s31
	s_nop 0
	global_load_lds_dwordx4 v[218:219], off
	s_mov_b32 m0, s33
	s_nop 0
	global_load_lds_dwordx4 v[220:221], off
	s_waitcnt vmcnt(8)
	s_waitcnt lgkmcnt(0)
	s_barrier
; #define PG8_STAGE(bufoff, gbase, voff) do { _Pragma("unroll") for (int _i = 0; _i < 2; ++_i) \
;         __builtin_amdgcn_global_load_lds((const unsigned*)((const char*)(gbase) + (voff)[_i]), (LAS unsigned*)(lds + (bufoff) + ldsw + _i * 8192), 16, 0, 0); } while (0)
; #define PG8_LDA(dst, b, h) do { _Pragma("unroll") for (int m = 0; m < 4; ++m) _Pragma("unroll") for (int k = 0; k < 2; ++k) dst[m][k] = *(const LAS bf16x8*)(lds + PG8_SA(b, h) + aoff + m * 2048 + k * 1024); } while (0)
; #define PG8_LDB(dst, b, h) do { _Pragma("unroll") for (int n = 0; n < 2; ++n) _Pragma("unroll") for (int k = 0; k < 2; ++k) dst[n][k] = *(const LAS bf16x8*)(lds + PG8_SB(b, h) + boff + n * 2048 + k * 1024); } while (0)
; #define PG8_MMA(ai, bj, At, Bt) do { __builtin_amdgcn_s_setprio(1); _Pragma("unroll") for (int m = 0; m < 4; ++m) _Pragma("unroll") for (int n = 0; n < 2; ++n) _Pragma("unroll") for (int k = 0; k < 2; ++k) \
;         acc[ai][bj][m][n] = __builtin_amdgcn_mfma_f32_16x16x32_bf16(Bt[n][k], At[m][k], acc[ai][bj][m][n], 0, 0, 0); __builtin_amdgcn_s_setprio(0); } while (0)
; #define PG8_WAIT_V(n) asm volatile("s_waitcnt vmcnt(" #n ")" ::: "memory")
; #define PG8_WAIT_L(n) asm volatile("s_waitcnt lgkmcnt(" #n ")" ::: "memory")
; #define PG8_BAR __builtin_amdgcn_s_barrier()
; #define PG8_SCHED __builtin_amdgcn_sched_barrier(0)
; template <class Epi, bool ALIGN_EPI, bool SP2 = PG8_SP2_DEFAULT>
; __device__ __forceinline__ void gemm_phase(LAS unsigned char* lds, const Gemm g, const StaticOrder& S, const Epi& E) {
;     ...
;             PG8_WAIT_V(8); PG8_WAIT_L(0); PG8_BAR; PG8_MMA(1, 0, At, B0); PG8_MMA(1, 1, At, B1); PG8_BAR; PG8_SCHED;
;             PG8_LDB(B0, 1, 0); PG8_LDB(B1, 1, 1); PG8_SCHED; PG8_LDA(At, 1, 0); PG8_STAGE(PG8_SA(0, 1), a2 + hstepA, voffA);
;             PG8_WAIT_V(8); PG8_WAIT_L(0); PG8_BAR; PG8_MMA(0, 0, At, B0); PG8_MMA(0, 1, At, B1); PG8_BAR; PG8_SCHED;
	v_mfma_f32_16x16x32_bf16 v[60:63], v[144:147], v[184:187], v[60:63]
	v_mfma_f32_16x16x32_bf16 v[56:59], v[160:163], v[184:187], v[56:59]
	v_mfma_f32_16x16x32_bf16 v[44:47], v[144:147], v[192:195], v[44:47]
	v_mfma_f32_16x16x32_bf16 v[40:43], v[160:163], v[192:195], v[40:43]
	v_mfma_f32_16x16x32_bf16 v[28:31], v[144:147], v[200:203], v[28:31]
	v_mfma_f32_16x16x32_bf16 v[24:27], v[160:163], v[200:203], v[24:27]
	v_mfma_f32_16x16x32_bf16 v[12:15], v[144:147], v[208:211], v[12:15]
	v_mfma_f32_16x16x32_bf16 v[8:11], v[160:163], v[208:211], v[8:11]
	v_mfma_f32_16x16x32_bf16 v[60:63], v[156:159], v[188:191], v[60:63]
	v_mfma_f32_16x16x32_bf16 v[56:59], v[164:167], v[188:191], v[56:59]
	v_mfma_f32_16x16x32_bf16 v[44:47], v[156:159], v[196:199], v[44:47]
	v_mfma_f32_16x16x32_bf16 v[40:43], v[164:167], v[196:199], v[40:43]
	v_mfma_f32_16x16x32_bf16 v[28:31], v[156:159], v[204:207], v[28:31]
	v_mfma_f32_16x16x32_bf16 v[24:27], v[164:167], v[204:207], v[24:27]
	v_mfma_f32_16x16x32_bf16 v[12:15], v[156:159], v[212:215], v[12:15]
	v_mfma_f32_16x16x32_bf16 v[8:11], v[164:167], v[212:215], v[8:11]
	v_mfma_f32_16x16x32_bf16 v[52:55], v[168:171], v[184:187], v[52:55]
	v_mfma_f32_16x16x32_bf16 v[48:51], v[176:179], v[184:187], v[48:51]
	v_mfma_f32_16x16x32_bf16 v[36:39], v[168:171], v[192:195], v[36:39]
	v_mfma_f32_16x16x32_bf16 v[32:35], v[176:179], v[192:195], v[32:35]
	v_mfma_f32_16x16x32_bf16 v[20:23], v[168:171], v[200:203], v[20:23]
	v_mfma_f32_16x16x32_bf16 v[16:19], v[176:179], v[200:203], v[16:19]
	v_mfma_f32_16x16x32_bf16 v[4:7], v[168:171], v[208:211], v[4:7]
	v_mfma_f32_16x16x32_bf16 v[0:3], v[176:179], v[208:211], v[0:3]
	v_mfma_f32_16x16x32_bf16 v[52:55], v[172:175], v[188:191], v[52:55]
	v_mfma_f32_16x16x32_bf16 v[48:51], v[180:183], v[188:191], v[48:51]
	v_mfma_f32_16x16x32_bf16 v[36:39], v[172:175], v[196:199], v[36:39]
	v_mfma_f32_16x16x32_bf16 v[32:35], v[180:183], v[196:199], v[32:35]
	v_mfma_f32_16x16x32_bf16 v[20:23], v[172:175], v[204:207], v[20:23]
	v_mfma_f32_16x16x32_bf16 v[16:19], v[180:183], v[204:207], v[16:19]
	v_mfma_f32_16x16x32_bf16 v[4:7], v[172:175], v[212:215], v[4:7]
	v_mfma_f32_16x16x32_bf16 v[0:3], v[180:183], v[212:215], v[0:3]
	s_barrier
	s_add_i32 s50, 0, 0x18000
	s_add_i32 s51, 0, 0x1c000
	v_add_u32_e32 v164, s50, v151
	v_add_u32_e32 v180, s51, v151
	ds_read_b128 v[144:147], v164
	ds_read_b128 v[156:159], v164 offset:1024
	ds_read_b128 v[160:163], v164 offset:2048
	ds_read_b128 v[164:167], v164 offset:3072
	ds_read_b128 v[168:171], v180
	ds_read_b128 v[172:175], v180 offset:1024
	ds_read_b128 v[176:179], v180 offset:2048
	ds_read_b128 v[180:183], v180 offset:3072
	s_add_u32 s20, s26, 0x2b0000
	s_addc_u32 s21, s27, 0
	s_mov_b32 m0, s34
	v_lshl_add_u64 v[222:223], s[20:21], 0, v[128:129]
	ds_read_b128 v[184:187], v155 offset:32768
	ds_read_b128 v[188:191], v155 offset:33792
	ds_read_b128 v[192:195], v155 offset:34816
	ds_read_b128 v[196:199], v155 offset:35840
	ds_read_b128 v[200:203], v155 offset:36864
	ds_read_b128 v[204:207], v155 offset:37888
	ds_read_b128 v[208:211], v155 offset:38912
	ds_read_b128 v[212:215], v155 offset:39936
	global_load_lds_dwordx4 v[222:223], off
	v_lshl_add_u64 v[222:223], s[20:21], 0, v[132:133]
	s_mov_b32 m0, s35
	s_nop 0
	global_load_lds_dwordx4 v[222:223], off
	s_waitcnt vmcnt(8)
	s_waitcnt lgkmcnt(0)
	s_barrier
	v_mfma_f32_16x16x32_bf16 v[124:127], v[144:147], v[184:187], v[124:127]
	v_mfma_f32_16x16x32_bf16 v[120:123], v[160:163], v[184:187], v[120:123]
	v_mfma_f32_16x16x32_bf16 v[108:111], v[144:147], v[192:195], v[108:111]
	v_mfma_f32_16x16x32_bf16 v[104:107], v[160:163], v[192:195], v[104:107]
	v_mfma_f32_16x16x32_bf16 v[92:95], v[144:147], v[200:203], v[92:95]
	v_mfma_f32_16x16x32_bf16 v[88:91], v[160:163], v[200:203], v[88:91]
	v_mfma_f32_16x16x32_bf16 v[76:79], v[144:147], v[208:211], v[76:79]
	v_mfma_f32_16x16x32_bf16 v[72:75], v[160:163], v[208:211], v[72:75]
	v_mfma_f32_16x16x32_bf16 v[124:127], v[156:159], v[188:191], v[124:127]
	v_mfma_f32_16x16x32_bf16 v[120:123], v[164:167], v[188:191], v[120:123]
	v_mfma_f32_16x16x32_bf16 v[108:111], v[156:159], v[196:199], v[108:111]
	v_mfma_f32_16x16x32_bf16 v[104:107], v[164:167], v[196:199], v[104:107]
	v_mfma_f32_16x16x32_bf16 v[92:95], v[156:159], v[204:207], v[92:95]
	v_mfma_f32_16x16x32_bf16 v[88:91], v[164:167], v[204:207], v[88:91]
	v_mfma_f32_16x16x32_bf16 v[76:79], v[156:159], v[212:215], v[76:79]
	v_mfma_f32_16x16x32_bf16 v[72:75], v[164:167], v[212:215], v[72:75]
	v_mfma_f32_16x16x32_bf16 v[116:119], v[168:171], v[184:187], v[116:119]
	v_mfma_f32_16x16x32_bf16 v[112:115], v[176:179], v[184:187], v[112:115]
	v_mfma_f32_16x16x32_bf16 v[100:103], v[168:171], v[192:195], v[100:103]
	v_mfma_f32_16x16x32_bf16 v[96:99], v[176:179], v[192:195], v[96:99]
	v_mfma_f32_16x16x32_bf16 v[84:87], v[168:171], v[200:203], v[84:87]
	v_mfma_f32_16x16x32_bf16 v[80:83], v[176:179], v[200:203], v[80:83]
	v_mfma_f32_16x16x32_bf16 v[68:71], v[168:171], v[208:211], v[68:71]
	v_mfma_f32_16x16x32_bf16 v[64:67], v[176:179], v[208:211], v[64:67]
	v_mfma_f32_16x16x32_bf16 v[116:119], v[172:175], v[188:191], v[116:119]
	v_mfma_f32_16x16x32_bf16 v[112:115], v[180:183], v[188:191], v[112:115]
	v_mfma_f32_16x16x32_bf16 v[100:103], v[172:175], v[196:199], v[100:103]
	v_mfma_f32_16x16x32_bf16 v[96:99], v[180:183], v[196:199], v[96:99]
	v_mfma_f32_16x16x32_bf16 v[84:87], v[172:175], v[204:207], v[84:87]
	v_mfma_f32_16x16x32_bf16 v[80:83], v[180:183], v[204:207], v[80:83]
	v_mfma_f32_16x16x32_bf16 v[68:71], v[172:175], v[212:215], v[68:71]
	v_mfma_f32_16x16x32_bf16 v[64:67], v[180:183], v[212:215], v[64:67]
	s_barrier
; #define PG8_STAGE(bufoff, gbase, voff) do { _Pragma("unroll") for (int _i = 0; _i < 2; ++_i) \
;         __builtin_amdgcn_global_load_lds((const unsigned*)((const char*)(gbase) + (voff)[_i]), (LAS unsigned*)(lds + (bufoff) + ldsw + _i * 8192), 16, 0, 0); } while (0)
; #define PG8_LDA(dst, b, h) do { _Pragma("unroll") for (int m = 0; m < 4; ++m) _Pragma("unroll") for (int k = 0; k < 2; ++k) dst[m][k] = *(const LAS bf16x8*)(lds + PG8_SA(b, h) + aoff + m * 2048 + k * 1024); } while (0)
; #define PG8_MMA(ai, bj, At, Bt) do { __builtin_amdgcn_s_setprio(1); _Pragma("unroll") for (int m = 0; m < 4; ++m) _Pragma("unroll") for (int n = 0; n < 2; ++n) _Pragma("unroll") for (int k = 0; k < 2; ++k) \
;         acc[ai][bj][m][n] = __builtin_amdgcn_mfma_f32_16x16x32_bf16(Bt[n][k], At[m][k], acc[ai][bj][m][n], 0, 0, 0); __builtin_amdgcn_s_setprio(0); } while (0)
; #define PG8_WAIT_V(n) asm volatile("s_waitcnt vmcnt(" #n ")" ::: "memory")
; #define PG8_WAIT_L(n) asm volatile("s_waitcnt lgkmcnt(" #n ")" ::: "memory")
; #define PG8_BAR __builtin_amdgcn_s_barrier()
; #define PG8_SCHED __builtin_amdgcn_sched_barrier(0)
; template <class Epi, bool ALIGN_EPI, bool SP2 = PG8_SP2_DEFAULT>
; __device__ __forceinline__ void gemm_phase(LAS unsigned char* lds, const Gemm g, const StaticOrder& S, const Epi& E) {
;     ...
;             PG8_LDA(At, 1, 1); PG8_STAGE(PG8_SB(1, 0), b3, voffB); PG8_STAGE(PG8_SB(1, 1), b3 + hstepB, voffB); PG8_STAGE(PG8_SA(1, 0), a3, voffA);
;             PG8_WAIT_V(8); PG8_WAIT_L(0); PG8_BAR; PG8_MMA(1, 0, At, B0); PG8_MMA(1, 1, At, B1); PG8_BAR; PG8_SCHED;
;     ...
;         if constexpr (ALIGN_EPI) { if (wr == 0) PG8_BAR; }
	s_add_i32 s20, s50, s28
	v_lshl_add_u64 v[148:149], v[148:149], 0, s[6:7]
	s_mov_b32 m0, s20
	ds_read_b128 v[184:187], v155 offset:49152
	ds_read_b128 v[188:191], v155 offset:50176
	ds_read_b128 v[192:195], v155 offset:51200
	ds_read_b128 v[196:199], v155 offset:52224
	ds_read_b128 v[200:203], v155 offset:53248
	ds_read_b128 v[204:207], v155 offset:54272
	ds_read_b128 v[208:211], v155 offset:55296
	ds_read_b128 v[212:215], v155 offset:56320
	global_load_lds_dwordx4 v[148:149], off
	s_add_i32 m0, s20, 0x2000
	s_add_u32 s20, s24, 0x2b0080
	v_lshl_add_u64 v[148:149], v[216:217], 0, s[6:7]
	s_addc_u32 s21, s25, 0
	s_add_i32 s24, s51, s28
	global_load_lds_dwordx4 v[148:149], off
	v_lshl_add_u64 v[148:149], s[20:21], 0, v[130:131]
	s_mov_b32 m0, s24
	s_nop 0
	global_load_lds_dwordx4 v[148:149], off
	v_lshl_add_u64 v[148:149], s[20:21], 0, v[134:135]
	s_add_i32 m0, s24, 0x2000
	s_nop 0
	global_load_lds_dwordx4 v[148:149], off
	v_lshl_add_u64 v[148:149], v[218:219], 0, s[6:7]
	s_mov_b32 m0, s37
	s_nop 0
	global_load_lds_dwordx4 v[148:149], off
	v_lshl_add_u64 v[148:149], v[220:221], 0, s[6:7]
	s_mov_b32 m0, s38
	s_nop 0
	global_load_lds_dwordx4 v[148:149], off
	s_waitcnt vmcnt(8)
	s_waitcnt lgkmcnt(0)
	s_barrier
	v_mfma_f32_16x16x32_bf16 v[60:63], v[144:147], v[184:187], v[60:63]
	v_mfma_f32_16x16x32_bf16 v[56:59], v[160:163], v[184:187], v[56:59]
	v_mfma_f32_16x16x32_bf16 v[44:47], v[144:147], v[192:195], v[44:47]
	v_mfma_f32_16x16x32_bf16 v[40:43], v[160:163], v[192:195], v[40:43]
	v_mfma_f32_16x16x32_bf16 v[28:31], v[144:147], v[200:203], v[28:31]
	v_mfma_f32_16x16x32_bf16 v[24:27], v[160:163], v[200:203], v[24:27]
	v_mfma_f32_16x16x32_bf16 v[12:15], v[144:147], v[208:211], v[12:15]
	v_mfma_f32_16x16x32_bf16 v[8:11], v[160:163], v[208:211], v[8:11]
	v_mfma_f32_16x16x32_bf16 v[60:63], v[156:159], v[188:191], v[60:63]
	v_mfma_f32_16x16x32_bf16 v[56:59], v[164:167], v[188:191], v[56:59]
	v_mfma_f32_16x16x32_bf16 v[44:47], v[156:159], v[196:199], v[44:47]
	v_mfma_f32_16x16x32_bf16 v[40:43], v[164:167], v[196:199], v[40:43]
	v_mfma_f32_16x16x32_bf16 v[28:31], v[156:159], v[204:207], v[28:31]
	v_mfma_f32_16x16x32_bf16 v[24:27], v[164:167], v[204:207], v[24:27]
	v_mfma_f32_16x16x32_bf16 v[12:15], v[156:159], v[212:215], v[12:15]
	v_mfma_f32_16x16x32_bf16 v[8:11], v[164:167], v[212:215], v[8:11]
	v_mfma_f32_16x16x32_bf16 v[52:55], v[168:171], v[184:187], v[52:55]
	v_mfma_f32_16x16x32_bf16 v[48:51], v[176:179], v[184:187], v[48:51]
	v_mfma_f32_16x16x32_bf16 v[36:39], v[168:171], v[192:195], v[36:39]
	v_mfma_f32_16x16x32_bf16 v[32:35], v[176:179], v[192:195], v[32:35]
	v_mfma_f32_16x16x32_bf16 v[20:23], v[168:171], v[200:203], v[20:23]
	v_mfma_f32_16x16x32_bf16 v[16:19], v[176:179], v[200:203], v[16:19]
	v_mfma_f32_16x16x32_bf16 v[4:7], v[168:171], v[208:211], v[4:7]
	v_mfma_f32_16x16x32_bf16 v[0:3], v[176:179], v[208:211], v[0:3]
	v_mfma_f32_16x16x32_bf16 v[52:55], v[172:175], v[188:191], v[52:55]
	v_mfma_f32_16x16x32_bf16 v[48:51], v[180:183], v[188:191], v[48:51]
	v_mfma_f32_16x16x32_bf16 v[36:39], v[172:175], v[196:199], v[36:39]
	v_mfma_f32_16x16x32_bf16 v[32:35], v[180:183], v[196:199], v[32:35]
	v_mfma_f32_16x16x32_bf16 v[20:23], v[172:175], v[204:207], v[20:23]
	v_mfma_f32_16x16x32_bf16 v[16:19], v[180:183], v[204:207], v[16:19]
	v_mfma_f32_16x16x32_bf16 v[4:7], v[172:175], v[212:215], v[4:7]
	v_mfma_f32_16x16x32_bf16 v[0:3], v[180:183], v[212:215], v[0:3]
	s_barrier
	s_add_i32 s49, s49, 2
	s_add_u32 s47, s47, 0x100
	s_addc_u32 s48, s48, 0
	s_cmpk_gt_u32 s49, 0xa9
	s_mov_b64 s[20:21], s[22:23]
	s_cbranch_scc0 .LBB0_804
	s_and_b64 vcc, exec, s[8:9]
	s_cbranch_vccz .LBB0_807
	s_barrier
